# 128x256 K-loops: six fragment reads up front, the other six reads and the DMA issue placed in the shadow of the first eight MFMAs (MFMA/LDS interleave)
# baseline (speedup 1.0000x reference)
; #define BLOAD(A_, B_, kt) do { _Pragma("unroll") for (int i = 0; i < 4; ++i) { \
;     A_[i] = *(const u32x4*)((const char*)Ap + (aoff + (unsigned)(32 * i * lda + (kt) * 64) * 2u)); B_[i] = *(const u32x4*)((const char*)Wt + (woff + (unsigned)(32 * i * K + (kt) * 64) * 2u)); } } while (0)
; #define BLOAD(A_, B_, kt) do { _Pragma("unroll") for (int i = 0; i < 4; ++i) { \
;     A_[i] = *(const u32x4*)((const char*)Ap + (aoff + (unsigned)(32 * i * lda + (kt) * 64) * 2u)); B_[i] = *(const u32x4*)((const char*)Wt + (woff + (unsigned)(32 * i * K + (kt) * 64) * 2u)); } } while (0)
; #define BSTORE(A_, B_, buf) do { _Pragma("unroll") for (int i = 0; i < 4; ++i) { \
;     *(u32x4*)&As[(buf) * GBUF + (srow + 32 * i) * LDT + sc8] = A_[i]; \
;     *(u32x4*)&Bs[(buf) * GBUF + (srow + 32 * i) * LDT + sc8] = B_[i]; } } while (0)
; template <int NK>
; DI void gemm_run(PF& pf, const u16* __restrict__ Ap, int lda, const u16* __restrict__ Wt, f32x16 (&acc)[2][2], char* smem) {
;     ...
;   __builtin_amdgcn_s_setprio(0);
;   __syncthreads();
;   BSTORE(pf.a0, pf.b0, 0);
;   BLOAD(pf.a0, pf.b0, 2);
;   __syncthreads();
; #pragma unroll
;   for (int kt = 0; kt < nk; kt += 2) {
;     BCOMP(0);
;     BSTORE(pf.a1, pf.b1, 1);
;     if (kt + 3 < nk) BLOAD(pf.a1, pf.b1, kt + 3);
;     __syncthreads();
;     BCOMP(1);
;     if (kt + 2 < nk) { BSTORE(pf.a0, pf.b0, 0); if (kt + 4 < nk) BLOAD(pf.a0, pf.b0, kt + 4); }
;     __syncthreads();
;   }
; DI void tile_ffn2(const Params& p, int l, const Chunk& ck, int tile, int next, PF& pf, char* smem) {
;     ...
;   { const u16* Ap; const u16* Wt; ffn2_ptrs(p, l, tile, Ap, Wt); gemm_run<64>(pf, Ap, 4096, Wt, acc, smem); }
.Lffn2_kloop:
	s_waitcnt vmcnt(6)
	s_barrier
	ds_read_b128 v[224:227], v126 offset:0
	ds_read_b128 v[240:243], v128 offset:0
	ds_read_b128 v[244:247], v128 offset:1024
	ds_read_b128 v[248:251], v128 offset:2048
	ds_read_b128 v[156:159], v128 offset:3072
	ds_read_b128 v[228:231], v126 offset:1024
	s_waitcnt lgkmcnt(4)
	v_mfma_f32_16x16x32_bf16 v[2:5], v[240:243], v[224:227], v[2:5]
	ds_read_b128 v[232:235], v126 offset:2048
	s_waitcnt lgkmcnt(4)
	v_mfma_f32_16x16x32_bf16 v[6:9], v[244:247], v[224:227], v[6:9]
	ds_read_b128 v[236:239], v126 offset:3072
	s_waitcnt lgkmcnt(4)
	v_mfma_f32_16x16x32_bf16 v[10:13], v[248:251], v[224:227], v[10:13]
	s_add_u32 m0, s16, 0xc000
	s_add_u32 s42, s42, 0x100000
	s_addc_u32 s43, s43, 0
	global_load_lds_dwordx4 v137, s[42:43]
	global_load_lds_dwordx4 v150, s[42:43] offset:1024
	s_add_u32 m0, s0, 0xc000
	s_add_u32 s30, s30, 0x10000
	s_addc_u32 s31, s31, 0
	global_load_lds_dwordx4 v151, s[30:31]
	global_load_lds_dwordx4 v152, s[30:31] offset:1024
	global_load_lds_dwordx4 v153, s[30:31] offset:2048
	global_load_lds_dwordx4 v154, s[30:31] offset:3072
	s_waitcnt lgkmcnt(3)
	v_mfma_f32_16x16x32_bf16 v[14:17], v[156:159], v[224:227], v[14:17]
	s_waitcnt lgkmcnt(2)
	v_mfma_f32_16x16x32_bf16 v[18:21], v[240:243], v[228:231], v[18:21]
	ds_read_b128 v[160:163], v128 offset:8192
	v_mfma_f32_16x16x32_bf16 v[22:25], v[244:247], v[228:231], v[22:25]
	ds_read_b128 v[164:167], v128 offset:9216
	v_mfma_f32_16x16x32_bf16 v[26:29], v[248:251], v[228:231], v[26:29]
	ds_read_b128 v[168:171], v128 offset:10240
	v_mfma_f32_16x16x32_bf16 v[30:33], v[156:159], v[228:231], v[30:33]
	ds_read_b128 v[122:125], v128 offset:11264
	s_waitcnt lgkmcnt(5)
	v_mfma_f32_16x16x32_bf16 v[34:37], v[240:243], v[232:235], v[34:37]
	v_mfma_f32_16x16x32_bf16 v[38:41], v[244:247], v[232:235], v[38:41]
	v_mfma_f32_16x16x32_bf16 v[42:45], v[248:251], v[232:235], v[42:45]
	v_mfma_f32_16x16x32_bf16 v[46:49], v[156:159], v[232:235], v[46:49]
	s_waitcnt lgkmcnt(4)
	v_mfma_f32_16x16x32_bf16 v[50:53], v[240:243], v[236:239], v[50:53]
	v_mfma_f32_16x16x32_bf16 v[54:57], v[244:247], v[236:239], v[54:57]
	v_mfma_f32_16x16x32_bf16 v[58:61], v[248:251], v[236:239], v[58:61]
	v_mfma_f32_16x16x32_bf16 v[62:65], v[156:159], v[236:239], v[62:65]
	s_waitcnt lgkmcnt(3)
	v_mfma_f32_16x16x32_bf16 v[74:77], v[160:163], v[224:227], v[74:77]
	s_waitcnt lgkmcnt(2)
	v_mfma_f32_16x16x32_bf16 v[78:81], v[164:167], v[224:227], v[78:81]
	s_waitcnt lgkmcnt(1)
	v_mfma_f32_16x16x32_bf16 v[82:85], v[168:171], v[224:227], v[82:85]
	s_waitcnt lgkmcnt(0)
	v_mfma_f32_16x16x32_bf16 v[86:89], v[122:125], v[224:227], v[86:89]
	v_mfma_f32_16x16x32_bf16 v[90:93], v[160:163], v[228:231], v[90:93]
	v_mfma_f32_16x16x32_bf16 v[94:97], v[164:167], v[228:231], v[94:97]
	v_mfma_f32_16x16x32_bf16 v[98:101], v[168:171], v[228:231], v[98:101]
	v_mfma_f32_16x16x32_bf16 v[102:105], v[122:125], v[228:231], v[102:105]
	v_mfma_f32_16x16x32_bf16 v[106:109], v[160:163], v[232:235], v[106:109]
	v_mfma_f32_16x16x32_bf16 v[110:113], v[164:167], v[232:235], v[110:113]
	v_mfma_f32_16x16x32_bf16 v[114:117], v[168:171], v[232:235], v[114:117]
	v_mfma_f32_16x16x32_bf16 v[118:121], v[122:125], v[232:235], v[118:121]
	v_mfma_f32_16x16x32_bf16 v[208:211], v[160:163], v[236:239], v[208:211]
	v_mfma_f32_16x16x32_bf16 v[212:215], v[164:167], v[236:239], v[212:215]
	v_mfma_f32_16x16x32_bf16 v[216:219], v[168:171], v[236:239], v[216:219]
	v_mfma_f32_16x16x32_bf16 v[220:223], v[122:125], v[236:239], v[220:223]
	s_waitcnt vmcnt(6)
	s_barrier
	ds_read_b128 v[224:227], v126 offset:24576
	ds_read_b128 v[240:243], v128 offset:24576
	ds_read_b128 v[244:247], v128 offset:25600
	ds_read_b128 v[248:251], v128 offset:26624
	ds_read_b128 v[156:159], v128 offset:27648
	ds_read_b128 v[228:231], v126 offset:25600
	s_waitcnt lgkmcnt(4)
	v_mfma_f32_16x16x32_bf16 v[2:5], v[240:243], v[224:227], v[2:5]
	ds_read_b128 v[232:235], v126 offset:26624
	s_waitcnt lgkmcnt(4)
	v_mfma_f32_16x16x32_bf16 v[6:9], v[244:247], v[224:227], v[6:9]
	ds_read_b128 v[236:239], v126 offset:27648
	s_waitcnt lgkmcnt(4)
	v_mfma_f32_16x16x32_bf16 v[10:13], v[248:251], v[224:227], v[10:13]
	s_add_u32 m0, s16, 0x0
	s_add_u32 s42, s42, 0x100000
	s_addc_u32 s43, s43, 0
	global_load_lds_dwordx4 v137, s[42:43]
	global_load_lds_dwordx4 v150, s[42:43] offset:1024
	s_add_u32 m0, s0, 0x0
	s_add_u32 s30, s30, 0x10000
	s_addc_u32 s31, s31, 0
	global_load_lds_dwordx4 v151, s[30:31]
	global_load_lds_dwordx4 v152, s[30:31] offset:1024
	global_load_lds_dwordx4 v153, s[30:31] offset:2048
	global_load_lds_dwordx4 v154, s[30:31] offset:3072
	s_waitcnt lgkmcnt(3)
	v_mfma_f32_16x16x32_bf16 v[14:17], v[156:159], v[224:227], v[14:17]
	s_waitcnt lgkmcnt(2)
	v_mfma_f32_16x16x32_bf16 v[18:21], v[240:243], v[228:231], v[18:21]
	ds_read_b128 v[160:163], v128 offset:32768
	v_mfma_f32_16x16x32_bf16 v[22:25], v[244:247], v[228:231], v[22:25]
	ds_read_b128 v[164:167], v128 offset:33792
	v_mfma_f32_16x16x32_bf16 v[26:29], v[248:251], v[228:231], v[26:29]
	ds_read_b128 v[168:171], v128 offset:34816
	v_mfma_f32_16x16x32_bf16 v[30:33], v[156:159], v[228:231], v[30:33]
	ds_read_b128 v[122:125], v128 offset:35840
	s_waitcnt lgkmcnt(5)
	v_mfma_f32_16x16x32_bf16 v[34:37], v[240:243], v[232:235], v[34:37]
	v_mfma_f32_16x16x32_bf16 v[38:41], v[244:247], v[232:235], v[38:41]
	v_mfma_f32_16x16x32_bf16 v[42:45], v[248:251], v[232:235], v[42:45]
	v_mfma_f32_16x16x32_bf16 v[46:49], v[156:159], v[232:235], v[46:49]
	s_waitcnt lgkmcnt(4)
	v_mfma_f32_16x16x32_bf16 v[50:53], v[240:243], v[236:239], v[50:53]
	v_mfma_f32_16x16x32_bf16 v[54:57], v[244:247], v[236:239], v[54:57]
	v_mfma_f32_16x16x32_bf16 v[58:61], v[248:251], v[236:239], v[58:61]
	v_mfma_f32_16x16x32_bf16 v[62:65], v[156:159], v[236:239], v[62:65]
	s_waitcnt lgkmcnt(3)
	v_mfma_f32_16x16x32_bf16 v[74:77], v[160:163], v[224:227], v[74:77]
	s_waitcnt lgkmcnt(2)
	v_mfma_f32_16x16x32_bf16 v[78:81], v[164:167], v[224:227], v[78:81]
	s_waitcnt lgkmcnt(1)
	v_mfma_f32_16x16x32_bf16 v[82:85], v[168:171], v[224:227], v[82:85]
	s_waitcnt lgkmcnt(0)
	v_mfma_f32_16x16x32_bf16 v[86:89], v[122:125], v[224:227], v[86:89]
	v_mfma_f32_16x16x32_bf16 v[90:93], v[160:163], v[228:231], v[90:93]
	v_mfma_f32_16x16x32_bf16 v[94:97], v[164:167], v[228:231], v[94:97]
	v_mfma_f32_16x16x32_bf16 v[98:101], v[168:171], v[228:231], v[98:101]
	v_mfma_f32_16x16x32_bf16 v[102:105], v[122:125], v[228:231], v[102:105]
	v_mfma_f32_16x16x32_bf16 v[106:109], v[160:163], v[232:235], v[106:109]
	v_mfma_f32_16x16x32_bf16 v[110:113], v[164:167], v[232:235], v[110:113]
	v_mfma_f32_16x16x32_bf16 v[114:117], v[168:171], v[232:235], v[114:117]
	v_mfma_f32_16x16x32_bf16 v[118:121], v[122:125], v[232:235], v[118:121]
	v_mfma_f32_16x16x32_bf16 v[208:211], v[160:163], v[236:239], v[208:211]
	v_mfma_f32_16x16x32_bf16 v[212:215], v[164:167], v[236:239], v[212:215]
	v_mfma_f32_16x16x32_bf16 v[216:219], v[168:171], v[236:239], v[216:219]
	v_mfma_f32_16x16x32_bf16 v[220:223], v[122:125], v[236:239], v[220:223]
	s_waitcnt vmcnt(6)
	s_barrier
; #define BLOAD(A_, B_, kt) do { _Pragma("unroll") for (int i = 0; i < 4; ++i) { \
;     A_[i] = *(const u32x4*)((const char*)Ap + (aoff + (unsigned)(32 * i * lda + (kt) * 64) * 2u)); B_[i] = *(const u32x4*)((const char*)Wt + (woff + (unsigned)(32 * i * K + (kt) * 64) * 2u)); } } while (0)
; #define BLOAD(A_, B_, kt) do { _Pragma("unroll") for (int i = 0; i < 4; ++i) { \
;     A_[i] = *(const u32x4*)((const char*)Ap + (aoff + (unsigned)(32 * i * lda + (kt) * 64) * 2u)); B_[i] = *(const u32x4*)((const char*)Wt + (woff + (unsigned)(32 * i * K + (kt) * 64) * 2u)); } } while (0)
; #define BSTORE(A_, B_, buf) do { _Pragma("unroll") for (int i = 0; i < 4; ++i) { \
;     *(u32x4*)&As[(buf) * GBUF + (srow + 32 * i) * LDT + sc8] = A_[i]; \
;     *(u32x4*)&Bs[(buf) * GBUF + (srow + 32 * i) * LDT + sc8] = B_[i]; } } while (0)
; template <int NK>
; DI void gemm_run(PF& pf, const u16* __restrict__ Ap, int lda, const u16* __restrict__ Wt, f32x16 (&acc)[2][2], char* smem) {
;     ...
;   __builtin_amdgcn_s_setprio(0);
;   __syncthreads();
;   BSTORE(pf.a0, pf.b0, 0);
;   BLOAD(pf.a0, pf.b0, 2);
;   __syncthreads();
; #pragma unroll
;   for (int kt = 0; kt < nk; kt += 2) {
;     BCOMP(0);
;     BSTORE(pf.a1, pf.b1, 1);
;     if (kt + 3 < nk) BLOAD(pf.a1, pf.b1, kt + 3);
;     __syncthreads();
;     BCOMP(1);
;     if (kt + 2 < nk) { BSTORE(pf.a0, pf.b0, 0); if (kt + 4 < nk) BLOAD(pf.a0, pf.b0, kt + 4); }
;     __syncthreads();
;   }
	ds_read_b128 v[224:227], v126 offset:49152
	ds_read_b128 v[240:243], v128 offset:49152
	ds_read_b128 v[244:247], v128 offset:50176
	ds_read_b128 v[248:251], v128 offset:51200
	ds_read_b128 v[156:159], v128 offset:52224
	ds_read_b128 v[228:231], v126 offset:50176
	s_waitcnt lgkmcnt(4)
	v_mfma_f32_16x16x32_bf16 v[2:5], v[240:243], v[224:227], v[2:5]
	ds_read_b128 v[232:235], v126 offset:51200
	s_waitcnt lgkmcnt(4)
	v_mfma_f32_16x16x32_bf16 v[6:9], v[244:247], v[224:227], v[6:9]
	ds_read_b128 v[236:239], v126 offset:52224
	s_waitcnt lgkmcnt(4)
	v_mfma_f32_16x16x32_bf16 v[10:13], v[248:251], v[224:227], v[10:13]
	s_add_u32 m0, s16, 0x6000
	s_add_u32 s42, s42, 0x100000
	s_addc_u32 s43, s43, 0
	global_load_lds_dwordx4 v137, s[42:43]
	global_load_lds_dwordx4 v150, s[42:43] offset:1024
	s_add_u32 m0, s0, 0x6000
	s_add_u32 s30, s30, 0x10000
	s_addc_u32 s31, s31, 0
	global_load_lds_dwordx4 v151, s[30:31]
	global_load_lds_dwordx4 v152, s[30:31] offset:1024
	global_load_lds_dwordx4 v153, s[30:31] offset:2048
	global_load_lds_dwordx4 v154, s[30:31] offset:3072
	s_waitcnt lgkmcnt(3)
	v_mfma_f32_16x16x32_bf16 v[14:17], v[156:159], v[224:227], v[14:17]
	s_waitcnt lgkmcnt(2)
	v_mfma_f32_16x16x32_bf16 v[18:21], v[240:243], v[228:231], v[18:21]
	ds_read_b128 v[160:163], v128 offset:57344
	v_mfma_f32_16x16x32_bf16 v[22:25], v[244:247], v[228:231], v[22:25]
	ds_read_b128 v[164:167], v128 offset:58368
	v_mfma_f32_16x16x32_bf16 v[26:29], v[248:251], v[228:231], v[26:29]
	ds_read_b128 v[168:171], v128 offset:59392
	v_mfma_f32_16x16x32_bf16 v[30:33], v[156:159], v[228:231], v[30:33]
	ds_read_b128 v[122:125], v128 offset:60416
	s_waitcnt lgkmcnt(5)
	v_mfma_f32_16x16x32_bf16 v[34:37], v[240:243], v[232:235], v[34:37]
	v_mfma_f32_16x16x32_bf16 v[38:41], v[244:247], v[232:235], v[38:41]
	v_mfma_f32_16x16x32_bf16 v[42:45], v[248:251], v[232:235], v[42:45]
	v_mfma_f32_16x16x32_bf16 v[46:49], v[156:159], v[232:235], v[46:49]
	s_waitcnt lgkmcnt(4)
	v_mfma_f32_16x16x32_bf16 v[50:53], v[240:243], v[236:239], v[50:53]
	v_mfma_f32_16x16x32_bf16 v[54:57], v[244:247], v[236:239], v[54:57]
	v_mfma_f32_16x16x32_bf16 v[58:61], v[248:251], v[236:239], v[58:61]
	v_mfma_f32_16x16x32_bf16 v[62:65], v[156:159], v[236:239], v[62:65]
	s_waitcnt lgkmcnt(3)
	v_mfma_f32_16x16x32_bf16 v[74:77], v[160:163], v[224:227], v[74:77]
	s_waitcnt lgkmcnt(2)
	v_mfma_f32_16x16x32_bf16 v[78:81], v[164:167], v[224:227], v[78:81]
	s_waitcnt lgkmcnt(1)
	v_mfma_f32_16x16x32_bf16 v[82:85], v[168:171], v[224:227], v[82:85]
	s_waitcnt lgkmcnt(0)
	v_mfma_f32_16x16x32_bf16 v[86:89], v[122:125], v[224:227], v[86:89]
	v_mfma_f32_16x16x32_bf16 v[90:93], v[160:163], v[228:231], v[90:93]
	v_mfma_f32_16x16x32_bf16 v[94:97], v[164:167], v[228:231], v[94:97]
	v_mfma_f32_16x16x32_bf16 v[98:101], v[168:171], v[228:231], v[98:101]
	v_mfma_f32_16x16x32_bf16 v[102:105], v[122:125], v[228:231], v[102:105]
	v_mfma_f32_16x16x32_bf16 v[106:109], v[160:163], v[232:235], v[106:109]
	v_mfma_f32_16x16x32_bf16 v[110:113], v[164:167], v[232:235], v[110:113]
	v_mfma_f32_16x16x32_bf16 v[114:117], v[168:171], v[232:235], v[114:117]
	v_mfma_f32_16x16x32_bf16 v[118:121], v[122:125], v[232:235], v[118:121]
	v_mfma_f32_16x16x32_bf16 v[208:211], v[160:163], v[236:239], v[208:211]
	v_mfma_f32_16x16x32_bf16 v[212:215], v[164:167], v[236:239], v[212:215]
	v_mfma_f32_16x16x32_bf16 v[216:219], v[168:171], v[236:239], v[216:219]
	v_mfma_f32_16x16x32_bf16 v[220:223], v[122:125], v[236:239], v[220:223]
	s_sub_u32 s46, s46, 1
	s_cmp_lg_u32 s46, 0
	s_cbranch_scc1 .Lffn2_kloop
	s_waitcnt vmcnt(6)
	s_barrier
; #define BLOAD(A_, B_, kt) do { _Pragma("unroll") for (int i = 0; i < 4; ++i) { \
;     A_[i] = *(const u32x4*)((const char*)Ap + (aoff + (unsigned)(32 * i * lda + (kt) * 64) * 2u)); B_[i] = *(const u32x4*)((const char*)Wt + (woff + (unsigned)(32 * i * K + (kt) * 64) * 2u)); } } while (0)
; #define BLOAD(A_, B_, kt) do { _Pragma("unroll") for (int i = 0; i < 4; ++i) { \
;     A_[i] = *(const u32x4*)((const char*)Ap + (aoff + (unsigned)(32 * i * lda + (kt) * 64) * 2u)); B_[i] = *(const u32x4*)((const char*)Wt + (woff + (unsigned)(32 * i * K + (kt) * 64) * 2u)); } } while (0)
; #define BSTORE(A_, B_, buf) do { _Pragma("unroll") for (int i = 0; i < 4; ++i) { \
;     *(u32x4*)&As[(buf) * GBUF + (srow + 32 * i) * LDT + sc8] = A_[i]; \
;     *(u32x4*)&Bs[(buf) * GBUF + (srow + 32 * i) * LDT + sc8] = B_[i]; } } while (0)
; template <int NK>
; DI void gemm_run(PF& pf, const u16* __restrict__ Ap, int lda, const u16* __restrict__ Wt, f32x16 (&acc)[2][2], char* smem) {
;     ...
;   __builtin_amdgcn_s_setprio(0);
;   __syncthreads();
;   BSTORE(pf.a0, pf.b0, 0);
;   BLOAD(pf.a0, pf.b0, 2);
;   __syncthreads();
; #pragma unroll
;   for (int kt = 0; kt < nk; kt += 2) {
;     BCOMP(0);
;     BSTORE(pf.a1, pf.b1, 1);
;     if (kt + 3 < nk) BLOAD(pf.a1, pf.b1, kt + 3);
;     __syncthreads();
;     BCOMP(1);
;     if (kt + 2 < nk) { BSTORE(pf.a0, pf.b0, 0); if (kt + 4 < nk) BLOAD(pf.a0, pf.b0, kt + 4); }
;     __syncthreads();
;   }
	ds_read_b128 v[224:227], v126 offset:0
	ds_read_b128 v[240:243], v128 offset:0
	ds_read_b128 v[244:247], v128 offset:1024
	ds_read_b128 v[248:251], v128 offset:2048
	ds_read_b128 v[156:159], v128 offset:3072
	ds_read_b128 v[228:231], v126 offset:1024
	s_waitcnt lgkmcnt(4)
	v_mfma_f32_16x16x32_bf16 v[2:5], v[240:243], v[224:227], v[2:5]
	ds_read_b128 v[232:235], v126 offset:2048
	s_waitcnt lgkmcnt(4)
	v_mfma_f32_16x16x32_bf16 v[6:9], v[244:247], v[224:227], v[6:9]
	ds_read_b128 v[236:239], v126 offset:3072
	s_waitcnt lgkmcnt(4)
	v_mfma_f32_16x16x32_bf16 v[10:13], v[248:251], v[224:227], v[10:13]
	s_waitcnt lgkmcnt(3)
	v_mfma_f32_16x16x32_bf16 v[14:17], v[156:159], v[224:227], v[14:17]
	s_waitcnt lgkmcnt(2)
	v_mfma_f32_16x16x32_bf16 v[18:21], v[240:243], v[228:231], v[18:21]
	ds_read_b128 v[160:163], v128 offset:8192
	v_mfma_f32_16x16x32_bf16 v[22:25], v[244:247], v[228:231], v[22:25]
	ds_read_b128 v[164:167], v128 offset:9216
	v_mfma_f32_16x16x32_bf16 v[26:29], v[248:251], v[228:231], v[26:29]
	ds_read_b128 v[168:171], v128 offset:10240
	v_mfma_f32_16x16x32_bf16 v[30:33], v[156:159], v[228:231], v[30:33]
	ds_read_b128 v[122:125], v128 offset:11264
	s_waitcnt lgkmcnt(5)
	v_mfma_f32_16x16x32_bf16 v[34:37], v[240:243], v[232:235], v[34:37]
	v_mfma_f32_16x16x32_bf16 v[38:41], v[244:247], v[232:235], v[38:41]
	v_mfma_f32_16x16x32_bf16 v[42:45], v[248:251], v[232:235], v[42:45]
	v_mfma_f32_16x16x32_bf16 v[46:49], v[156:159], v[232:235], v[46:49]
	s_waitcnt lgkmcnt(4)
	v_mfma_f32_16x16x32_bf16 v[50:53], v[240:243], v[236:239], v[50:53]
	v_mfma_f32_16x16x32_bf16 v[54:57], v[244:247], v[236:239], v[54:57]
	v_mfma_f32_16x16x32_bf16 v[58:61], v[248:251], v[236:239], v[58:61]
	v_mfma_f32_16x16x32_bf16 v[62:65], v[156:159], v[236:239], v[62:65]
	s_waitcnt lgkmcnt(3)
	v_mfma_f32_16x16x32_bf16 v[74:77], v[160:163], v[224:227], v[74:77]
	s_waitcnt lgkmcnt(2)
	v_mfma_f32_16x16x32_bf16 v[78:81], v[164:167], v[224:227], v[78:81]
	s_waitcnt lgkmcnt(1)
	v_mfma_f32_16x16x32_bf16 v[82:85], v[168:171], v[224:227], v[82:85]
	s_waitcnt lgkmcnt(0)
	v_mfma_f32_16x16x32_bf16 v[86:89], v[122:125], v[224:227], v[86:89]
	v_mfma_f32_16x16x32_bf16 v[90:93], v[160:163], v[228:231], v[90:93]
	v_mfma_f32_16x16x32_bf16 v[94:97], v[164:167], v[228:231], v[94:97]
	v_mfma_f32_16x16x32_bf16 v[98:101], v[168:171], v[228:231], v[98:101]
	v_mfma_f32_16x16x32_bf16 v[102:105], v[122:125], v[228:231], v[102:105]
	v_mfma_f32_16x16x32_bf16 v[106:109], v[160:163], v[232:235], v[106:109]
	v_mfma_f32_16x16x32_bf16 v[110:113], v[164:167], v[232:235], v[110:113]
	v_mfma_f32_16x16x32_bf16 v[114:117], v[168:171], v[232:235], v[114:117]
	v_mfma_f32_16x16x32_bf16 v[118:121], v[122:125], v[232:235], v[118:121]
	v_mfma_f32_16x16x32_bf16 v[208:211], v[160:163], v[236:239], v[208:211]
	v_mfma_f32_16x16x32_bf16 v[212:215], v[164:167], v[236:239], v[212:215]
	v_mfma_f32_16x16x32_bf16 v[216:219], v[168:171], v[236:239], v[216:219]
	v_mfma_f32_16x16x32_bf16 v[220:223], v[122:125], v[236:239], v[220:223]
	s_waitcnt vmcnt(0)
	s_barrier
	ds_read_b128 v[224:227], v126 offset:24576
	ds_read_b128 v[240:243], v128 offset:24576
	ds_read_b128 v[244:247], v128 offset:25600
	ds_read_b128 v[248:251], v128 offset:26624
	ds_read_b128 v[156:159], v128 offset:27648
	ds_read_b128 v[228:231], v126 offset:25600
	s_waitcnt lgkmcnt(4)
	v_mfma_f32_16x16x32_bf16 v[2:5], v[240:243], v[224:227], v[2:5]
	ds_read_b128 v[232:235], v126 offset:26624
	s_waitcnt lgkmcnt(4)
	v_mfma_f32_16x16x32_bf16 v[6:9], v[244:247], v[224:227], v[6:9]
	ds_read_b128 v[236:239], v126 offset:27648
	s_waitcnt lgkmcnt(4)
	v_mfma_f32_16x16x32_bf16 v[10:13], v[248:251], v[224:227], v[10:13]
	s_waitcnt lgkmcnt(3)
	v_mfma_f32_16x16x32_bf16 v[14:17], v[156:159], v[224:227], v[14:17]
	s_waitcnt lgkmcnt(2)
	v_mfma_f32_16x16x32_bf16 v[18:21], v[240:243], v[228:231], v[18:21]
	ds_read_b128 v[160:163], v128 offset:32768
	v_mfma_f32_16x16x32_bf16 v[22:25], v[244:247], v[228:231], v[22:25]
	ds_read_b128 v[164:167], v128 offset:33792
	v_mfma_f32_16x16x32_bf16 v[26:29], v[248:251], v[228:231], v[26:29]
	ds_read_b128 v[168:171], v128 offset:34816
	v_mfma_f32_16x16x32_bf16 v[30:33], v[156:159], v[228:231], v[30:33]
	ds_read_b128 v[122:125], v128 offset:35840
	s_waitcnt lgkmcnt(5)
	v_mfma_f32_16x16x32_bf16 v[34:37], v[240:243], v[232:235], v[34:37]
	v_mfma_f32_16x16x32_bf16 v[38:41], v[244:247], v[232:235], v[38:41]
	v_mfma_f32_16x16x32_bf16 v[42:45], v[248:251], v[232:235], v[42:45]
	v_mfma_f32_16x16x32_bf16 v[46:49], v[156:159], v[232:235], v[46:49]
	s_waitcnt lgkmcnt(4)
	v_mfma_f32_16x16x32_bf16 v[50:53], v[240:243], v[236:239], v[50:53]
	v_mfma_f32_16x16x32_bf16 v[54:57], v[244:247], v[236:239], v[54:57]
	v_mfma_f32_16x16x32_bf16 v[58:61], v[248:251], v[236:239], v[58:61]
	v_mfma_f32_16x16x32_bf16 v[62:65], v[156:159], v[236:239], v[62:65]
	s_waitcnt lgkmcnt(3)
	v_mfma_f32_16x16x32_bf16 v[74:77], v[160:163], v[224:227], v[74:77]
	s_waitcnt lgkmcnt(2)
	v_mfma_f32_16x16x32_bf16 v[78:81], v[164:167], v[224:227], v[78:81]
	s_waitcnt lgkmcnt(1)
	v_mfma_f32_16x16x32_bf16 v[82:85], v[168:171], v[224:227], v[82:85]
	s_waitcnt lgkmcnt(0)
	v_mfma_f32_16x16x32_bf16 v[86:89], v[122:125], v[224:227], v[86:89]
	v_mfma_f32_16x16x32_bf16 v[90:93], v[160:163], v[228:231], v[90:93]
	v_mfma_f32_16x16x32_bf16 v[94:97], v[164:167], v[228:231], v[94:97]
	v_mfma_f32_16x16x32_bf16 v[98:101], v[168:171], v[228:231], v[98:101]
	v_mfma_f32_16x16x32_bf16 v[102:105], v[122:125], v[228:231], v[102:105]
	v_mfma_f32_16x16x32_bf16 v[106:109], v[160:163], v[232:235], v[106:109]
	v_mfma_f32_16x16x32_bf16 v[110:113], v[164:167], v[232:235], v[110:113]
	v_mfma_f32_16x16x32_bf16 v[114:117], v[168:171], v[232:235], v[114:117]
	v_mfma_f32_16x16x32_bf16 v[118:121], v[122:125], v[232:235], v[118:121]
	v_mfma_f32_16x16x32_bf16 v[208:211], v[160:163], v[236:239], v[208:211]
	v_mfma_f32_16x16x32_bf16 v[212:215], v[164:167], v[236:239], v[212:215]
	v_mfma_f32_16x16x32_bf16 v[216:219], v[168:171], v[236:239], v[216:219]
	v_mfma_f32_16x16x32_bf16 v[220:223], v[122:125], v[236:239], v[220:223]
	s_barrier
	s_mov_b32 s16, 0

; #define BLOAD(A_, B_, kt) do { _Pragma("unroll") for (int i = 0; i < 4; ++i) { \
;     A_[i] = *(const u32x4*)((const char*)Ap + (aoff + (unsigned)(32 * i * lda + (kt) * 64) * 2u)); B_[i] = *(const u32x4*)((const char*)Wt + (woff + (unsigned)(32 * i * K + (kt) * 64) * 2u)); } } while (0)
; #define BLOAD(A_, B_, kt) do { _Pragma("unroll") for (int i = 0; i < 4; ++i) { \
;     A_[i] = *(const u32x4*)((const char*)Ap + (aoff + (unsigned)(32 * i * lda + (kt) * 64) * 2u)); B_[i] = *(const u32x4*)((const char*)Wt + (woff + (unsigned)(32 * i * K + (kt) * 64) * 2u)); } } while (0)
; #define BSTORE(A_, B_, buf) do { _Pragma("unroll") for (int i = 0; i < 4; ++i) { \
;     *(u32x4*)&As[(buf) * GBUF + (srow + 32 * i) * LDT + sc8] = A_[i]; \
;     *(u32x4*)&Bs[(buf) * GBUF + (srow + 32 * i) * LDT + sc8] = B_[i]; } } while (0)
; template <int NK>
; DI void gemm_run(PF& pf, const u16* __restrict__ Ap, int lda, const u16* __restrict__ Wt, f32x16 (&acc)[2][2], char* smem) {
;     ...
;   __builtin_amdgcn_s_setprio(0);
;   __syncthreads();
;   BSTORE(pf.a0, pf.b0, 0);
;   BLOAD(pf.a0, pf.b0, 2);
;   __syncthreads();
; #pragma unroll
;   for (int kt = 0; kt < nk; kt += 2) {
;     BCOMP(0);
;     BSTORE(pf.a1, pf.b1, 1);
;     if (kt + 3 < nk) BLOAD(pf.a1, pf.b1, kt + 3);
;     __syncthreads();
;     BCOMP(1);
;     if (kt + 2 < nk) { BSTORE(pf.a0, pf.b0, 0); if (kt + 4 < nk) BLOAD(pf.a0, pf.b0, kt + 4); }
;     __syncthreads();
;   }
.Lffn1_kloop:
	s_waitcnt vmcnt(6)
	s_barrier
	ds_read_b128 v[208:211], v138 offset:0
	ds_read_b128 v[224:227], v140 offset:0
	ds_read_b128 v[228:231], v140 offset:1024
	ds_read_b128 v[232:235], v140 offset:2048
	ds_read_b128 v[236:239], v140 offset:3072
	ds_read_b128 v[212:215], v138 offset:1024
	s_waitcnt lgkmcnt(4)
	v_mfma_f32_16x16x32_bf16 v[2:5], v[224:227], v[208:211], v[2:5]
	ds_read_b128 v[216:219], v138 offset:2048
	s_waitcnt lgkmcnt(4)
	v_mfma_f32_16x16x32_bf16 v[6:9], v[228:231], v[208:211], v[6:9]
	ds_read_b128 v[220:223], v138 offset:3072
	s_waitcnt lgkmcnt(4)
	v_mfma_f32_16x16x32_bf16 v[10:13], v[232:235], v[208:211], v[10:13]
	s_add_u32 m0, s42, 0xc000
	s_add_u32 s28, s28, 0x100000
	s_addc_u32 s29, s29, 0
	global_load_lds_dwordx4 v142, s[28:29]
	global_load_lds_dwordx4 v143, s[28:29] offset:1024
	s_add_u32 m0, s43, 0xc000
	s_add_u32 s30, s30, 0x40000
	s_addc_u32 s31, s31, 0
	global_load_lds_dwordx4 v144, s[30:31]
	global_load_lds_dwordx4 v145, s[30:31] offset:1024
	global_load_lds_dwordx4 v146, s[30:31] offset:2048
	global_load_lds_dwordx4 v147, s[30:31] offset:3072
	s_waitcnt lgkmcnt(3)
	v_mfma_f32_16x16x32_bf16 v[14:17], v[236:239], v[208:211], v[14:17]
	s_waitcnt lgkmcnt(2)
	v_mfma_f32_16x16x32_bf16 v[18:21], v[224:227], v[212:215], v[18:21]
	ds_read_b128 v[240:243], v140 offset:8192
	v_mfma_f32_16x16x32_bf16 v[22:25], v[228:231], v[212:215], v[22:25]
	ds_read_b128 v[244:247], v140 offset:9216
	v_mfma_f32_16x16x32_bf16 v[26:29], v[232:235], v[212:215], v[26:29]
	ds_read_b128 v[248:251], v140 offset:10240
	v_mfma_f32_16x16x32_bf16 v[30:33], v[236:239], v[212:215], v[30:33]
	ds_read_b128 v[156:159], v140 offset:11264
	s_waitcnt lgkmcnt(5)
	v_mfma_f32_16x16x32_bf16 v[34:37], v[224:227], v[216:219], v[34:37]
	v_mfma_f32_16x16x32_bf16 v[38:41], v[228:231], v[216:219], v[38:41]
	v_mfma_f32_16x16x32_bf16 v[42:45], v[232:235], v[216:219], v[42:45]
	v_mfma_f32_16x16x32_bf16 v[46:49], v[236:239], v[216:219], v[46:49]
	s_waitcnt lgkmcnt(4)
	v_mfma_f32_16x16x32_bf16 v[50:53], v[224:227], v[220:223], v[50:53]
	v_mfma_f32_16x16x32_bf16 v[54:57], v[228:231], v[220:223], v[54:57]
	v_mfma_f32_16x16x32_bf16 v[58:61], v[232:235], v[220:223], v[58:61]
	v_mfma_f32_16x16x32_bf16 v[62:65], v[236:239], v[220:223], v[62:65]
	s_waitcnt lgkmcnt(3)
	v_mfma_f32_16x16x32_bf16 v[74:77], v[240:243], v[208:211], v[74:77]
	s_waitcnt lgkmcnt(2)
	v_mfma_f32_16x16x32_bf16 v[78:81], v[244:247], v[208:211], v[78:81]
	s_waitcnt lgkmcnt(1)
	v_mfma_f32_16x16x32_bf16 v[82:85], v[248:251], v[208:211], v[82:85]
	s_waitcnt lgkmcnt(0)
	v_mfma_f32_16x16x32_bf16 v[86:89], v[156:159], v[208:211], v[86:89]
	v_mfma_f32_16x16x32_bf16 v[90:93], v[240:243], v[212:215], v[90:93]
	v_mfma_f32_16x16x32_bf16 v[94:97], v[244:247], v[212:215], v[94:97]
	v_mfma_f32_16x16x32_bf16 v[98:101], v[248:251], v[212:215], v[98:101]
	v_mfma_f32_16x16x32_bf16 v[102:105], v[156:159], v[212:215], v[102:105]
	v_mfma_f32_16x16x32_bf16 v[106:109], v[240:243], v[216:219], v[106:109]
	v_mfma_f32_16x16x32_bf16 v[110:113], v[244:247], v[216:219], v[110:113]
	v_mfma_f32_16x16x32_bf16 v[114:117], v[248:251], v[216:219], v[114:117]
	v_mfma_f32_16x16x32_bf16 v[118:121], v[156:159], v[216:219], v[118:121]
	v_mfma_f32_16x16x32_bf16 v[122:125], v[240:243], v[220:223], v[122:125]
	v_mfma_f32_16x16x32_bf16 v[126:129], v[244:247], v[220:223], v[126:129]
	v_mfma_f32_16x16x32_bf16 v[130:133], v[248:251], v[220:223], v[130:133]
	v_mfma_f32_16x16x32_bf16 v[134:137], v[156:159], v[220:223], v[134:137]
	s_waitcnt vmcnt(6)
	s_barrier
	ds_read_b128 v[208:211], v138 offset:24576
	ds_read_b128 v[224:227], v140 offset:24576
	ds_read_b128 v[228:231], v140 offset:25600
	ds_read_b128 v[232:235], v140 offset:26624
	ds_read_b128 v[236:239], v140 offset:27648
	ds_read_b128 v[212:215], v138 offset:25600
	s_waitcnt lgkmcnt(4)
	v_mfma_f32_16x16x32_bf16 v[2:5], v[224:227], v[208:211], v[2:5]
	ds_read_b128 v[216:219], v138 offset:26624
	s_waitcnt lgkmcnt(4)
	v_mfma_f32_16x16x32_bf16 v[6:9], v[228:231], v[208:211], v[6:9]
	ds_read_b128 v[220:223], v138 offset:27648
	s_waitcnt lgkmcnt(4)
	v_mfma_f32_16x16x32_bf16 v[10:13], v[232:235], v[208:211], v[10:13]
	s_add_u32 m0, s42, 0x0
	s_add_u32 s28, s28, 0x100000
	s_addc_u32 s29, s29, 0
	global_load_lds_dwordx4 v142, s[28:29]
	global_load_lds_dwordx4 v143, s[28:29] offset:1024
	s_add_u32 m0, s43, 0x0
	s_add_u32 s30, s30, 0x40000
	s_addc_u32 s31, s31, 0
	global_load_lds_dwordx4 v144, s[30:31]
	global_load_lds_dwordx4 v145, s[30:31] offset:1024
	global_load_lds_dwordx4 v146, s[30:31] offset:2048
	global_load_lds_dwordx4 v147, s[30:31] offset:3072
	s_waitcnt lgkmcnt(3)
	v_mfma_f32_16x16x32_bf16 v[14:17], v[236:239], v[208:211], v[14:17]
	s_waitcnt lgkmcnt(2)
	v_mfma_f32_16x16x32_bf16 v[18:21], v[224:227], v[212:215], v[18:21]
	ds_read_b128 v[240:243], v140 offset:32768
	v_mfma_f32_16x16x32_bf16 v[22:25], v[228:231], v[212:215], v[22:25]
	ds_read_b128 v[244:247], v140 offset:33792
	v_mfma_f32_16x16x32_bf16 v[26:29], v[232:235], v[212:215], v[26:29]
	ds_read_b128 v[248:251], v140 offset:34816
	v_mfma_f32_16x16x32_bf16 v[30:33], v[236:239], v[212:215], v[30:33]
	ds_read_b128 v[156:159], v140 offset:35840
	s_waitcnt lgkmcnt(5)
	v_mfma_f32_16x16x32_bf16 v[34:37], v[224:227], v[216:219], v[34:37]
	v_mfma_f32_16x16x32_bf16 v[38:41], v[228:231], v[216:219], v[38:41]
	v_mfma_f32_16x16x32_bf16 v[42:45], v[232:235], v[216:219], v[42:45]
	v_mfma_f32_16x16x32_bf16 v[46:49], v[236:239], v[216:219], v[46:49]
	s_waitcnt lgkmcnt(4)
	v_mfma_f32_16x16x32_bf16 v[50:53], v[224:227], v[220:223], v[50:53]
	v_mfma_f32_16x16x32_bf16 v[54:57], v[228:231], v[220:223], v[54:57]
	v_mfma_f32_16x16x32_bf16 v[58:61], v[232:235], v[220:223], v[58:61]
	v_mfma_f32_16x16x32_bf16 v[62:65], v[236:239], v[220:223], v[62:65]
	s_waitcnt lgkmcnt(3)
	v_mfma_f32_16x16x32_bf16 v[74:77], v[240:243], v[208:211], v[74:77]
	s_waitcnt lgkmcnt(2)
	v_mfma_f32_16x16x32_bf16 v[78:81], v[244:247], v[208:211], v[78:81]
	s_waitcnt lgkmcnt(1)
	v_mfma_f32_16x16x32_bf16 v[82:85], v[248:251], v[208:211], v[82:85]
	s_waitcnt lgkmcnt(0)
	v_mfma_f32_16x16x32_bf16 v[86:89], v[156:159], v[208:211], v[86:89]
	v_mfma_f32_16x16x32_bf16 v[90:93], v[240:243], v[212:215], v[90:93]
	v_mfma_f32_16x16x32_bf16 v[94:97], v[244:247], v[212:215], v[94:97]
	v_mfma_f32_16x16x32_bf16 v[98:101], v[248:251], v[212:215], v[98:101]
	v_mfma_f32_16x16x32_bf16 v[102:105], v[156:159], v[212:215], v[102:105]
	v_mfma_f32_16x16x32_bf16 v[106:109], v[240:243], v[216:219], v[106:109]
	v_mfma_f32_16x16x32_bf16 v[110:113], v[244:247], v[216:219], v[110:113]
	v_mfma_f32_16x16x32_bf16 v[114:117], v[248:251], v[216:219], v[114:117]
	v_mfma_f32_16x16x32_bf16 v[118:121], v[156:159], v[216:219], v[118:121]
	v_mfma_f32_16x16x32_bf16 v[122:125], v[240:243], v[220:223], v[122:125]
	v_mfma_f32_16x16x32_bf16 v[126:129], v[244:247], v[220:223], v[126:129]
	v_mfma_f32_16x16x32_bf16 v[130:133], v[248:251], v[220:223], v[130:133]
	v_mfma_f32_16x16x32_bf16 v[134:137], v[156:159], v[220:223], v[134:137]
	s_waitcnt vmcnt(6)
	s_barrier
; #define BLOAD(A_, B_, kt) do { _Pragma("unroll") for (int i = 0; i < 4; ++i) { \
;     A_[i] = *(const u32x4*)((const char*)Ap + (aoff + (unsigned)(32 * i * lda + (kt) * 64) * 2u)); B_[i] = *(const u32x4*)((const char*)Wt + (woff + (unsigned)(32 * i * K + (kt) * 64) * 2u)); } } while (0)
; #define BLOAD(A_, B_, kt) do { _Pragma("unroll") for (int i = 0; i < 4; ++i) { \
;     A_[i] = *(const u32x4*)((const char*)Ap + (aoff + (unsigned)(32 * i * lda + (kt) * 64) * 2u)); B_[i] = *(const u32x4*)((const char*)Wt + (woff + (unsigned)(32 * i * K + (kt) * 64) * 2u)); } } while (0)
; #define BSTORE(A_, B_, buf) do { _Pragma("unroll") for (int i = 0; i < 4; ++i) { \
;     *(u32x4*)&As[(buf) * GBUF + (srow + 32 * i) * LDT + sc8] = A_[i]; \
;     *(u32x4*)&Bs[(buf) * GBUF + (srow + 32 * i) * LDT + sc8] = B_[i]; } } while (0)
; template <int NK>
; DI void gemm_run(PF& pf, const u16* __restrict__ Ap, int lda, const u16* __restrict__ Wt, f32x16 (&acc)[2][2], char* smem) {
;     ...
;   __builtin_amdgcn_s_setprio(0);
;   __syncthreads();
;   BSTORE(pf.a0, pf.b0, 0);
;   BLOAD(pf.a0, pf.b0, 2);
;   __syncthreads();
; #pragma unroll
;   for (int kt = 0; kt < nk; kt += 2) {
;     BCOMP(0);
;     BSTORE(pf.a1, pf.b1, 1);
;     if (kt + 3 < nk) BLOAD(pf.a1, pf.b1, kt + 3);
;     __syncthreads();
;     BCOMP(1);
;     if (kt + 2 < nk) { BSTORE(pf.a0, pf.b0, 0); if (kt + 4 < nk) BLOAD(pf.a0, pf.b0, kt + 4); }
;     __syncthreads();
;   }
	ds_read_b128 v[208:211], v138 offset:49152
	ds_read_b128 v[224:227], v140 offset:49152
	ds_read_b128 v[228:231], v140 offset:50176
	ds_read_b128 v[232:235], v140 offset:51200
	ds_read_b128 v[236:239], v140 offset:52224
	ds_read_b128 v[212:215], v138 offset:50176
	s_waitcnt lgkmcnt(4)
	v_mfma_f32_16x16x32_bf16 v[2:5], v[224:227], v[208:211], v[2:5]
	ds_read_b128 v[216:219], v138 offset:51200
	s_waitcnt lgkmcnt(4)
	v_mfma_f32_16x16x32_bf16 v[6:9], v[228:231], v[208:211], v[6:9]
	ds_read_b128 v[220:223], v138 offset:52224
	s_waitcnt lgkmcnt(4)
	v_mfma_f32_16x16x32_bf16 v[10:13], v[232:235], v[208:211], v[10:13]
	s_add_u32 m0, s42, 0x6000
	s_add_u32 s28, s28, 0x100000
	s_addc_u32 s29, s29, 0
	global_load_lds_dwordx4 v142, s[28:29]
	global_load_lds_dwordx4 v143, s[28:29] offset:1024
	s_add_u32 m0, s43, 0x6000
	s_add_u32 s30, s30, 0x40000
	s_addc_u32 s31, s31, 0
	global_load_lds_dwordx4 v144, s[30:31]
	global_load_lds_dwordx4 v145, s[30:31] offset:1024
	global_load_lds_dwordx4 v146, s[30:31] offset:2048
	global_load_lds_dwordx4 v147, s[30:31] offset:3072
	s_waitcnt lgkmcnt(3)
	v_mfma_f32_16x16x32_bf16 v[14:17], v[236:239], v[208:211], v[14:17]
	s_waitcnt lgkmcnt(2)
	v_mfma_f32_16x16x32_bf16 v[18:21], v[224:227], v[212:215], v[18:21]
	ds_read_b128 v[240:243], v140 offset:57344
	v_mfma_f32_16x16x32_bf16 v[22:25], v[228:231], v[212:215], v[22:25]
	ds_read_b128 v[244:247], v140 offset:58368
	v_mfma_f32_16x16x32_bf16 v[26:29], v[232:235], v[212:215], v[26:29]
	ds_read_b128 v[248:251], v140 offset:59392
	v_mfma_f32_16x16x32_bf16 v[30:33], v[236:239], v[212:215], v[30:33]
	ds_read_b128 v[156:159], v140 offset:60416
	s_waitcnt lgkmcnt(5)
	v_mfma_f32_16x16x32_bf16 v[34:37], v[224:227], v[216:219], v[34:37]
	v_mfma_f32_16x16x32_bf16 v[38:41], v[228:231], v[216:219], v[38:41]
	v_mfma_f32_16x16x32_bf16 v[42:45], v[232:235], v[216:219], v[42:45]
	v_mfma_f32_16x16x32_bf16 v[46:49], v[236:239], v[216:219], v[46:49]
	s_waitcnt lgkmcnt(4)
	v_mfma_f32_16x16x32_bf16 v[50:53], v[224:227], v[220:223], v[50:53]
	v_mfma_f32_16x16x32_bf16 v[54:57], v[228:231], v[220:223], v[54:57]
	v_mfma_f32_16x16x32_bf16 v[58:61], v[232:235], v[220:223], v[58:61]
	v_mfma_f32_16x16x32_bf16 v[62:65], v[236:239], v[220:223], v[62:65]
	s_waitcnt lgkmcnt(3)
	v_mfma_f32_16x16x32_bf16 v[74:77], v[240:243], v[208:211], v[74:77]
	s_waitcnt lgkmcnt(2)
	v_mfma_f32_16x16x32_bf16 v[78:81], v[244:247], v[208:211], v[78:81]
	s_waitcnt lgkmcnt(1)
	v_mfma_f32_16x16x32_bf16 v[82:85], v[248:251], v[208:211], v[82:85]
	s_waitcnt lgkmcnt(0)
	v_mfma_f32_16x16x32_bf16 v[86:89], v[156:159], v[208:211], v[86:89]
	v_mfma_f32_16x16x32_bf16 v[90:93], v[240:243], v[212:215], v[90:93]
	v_mfma_f32_16x16x32_bf16 v[94:97], v[244:247], v[212:215], v[94:97]
	v_mfma_f32_16x16x32_bf16 v[98:101], v[248:251], v[212:215], v[98:101]
	v_mfma_f32_16x16x32_bf16 v[102:105], v[156:159], v[212:215], v[102:105]
	v_mfma_f32_16x16x32_bf16 v[106:109], v[240:243], v[216:219], v[106:109]
	v_mfma_f32_16x16x32_bf16 v[110:113], v[244:247], v[216:219], v[110:113]
	v_mfma_f32_16x16x32_bf16 v[114:117], v[248:251], v[216:219], v[114:117]
	v_mfma_f32_16x16x32_bf16 v[118:121], v[156:159], v[216:219], v[118:121]
	v_mfma_f32_16x16x32_bf16 v[122:125], v[240:243], v[220:223], v[122:125]
	v_mfma_f32_16x16x32_bf16 v[126:129], v[244:247], v[220:223], v[126:129]
	v_mfma_f32_16x16x32_bf16 v[130:133], v[248:251], v[220:223], v[130:133]
	v_mfma_f32_16x16x32_bf16 v[134:137], v[156:159], v[220:223], v[134:137]
	s_sub_u32 s46, s46, 1
	s_cmp_lg_u32 s46, 0
	s_cbranch_scc1 .Lffn1_kloop
	s_waitcnt vmcnt(6)
	s_barrier
; #define BLOAD(A_, B_, kt) do { _Pragma("unroll") for (int i = 0; i < 4; ++i) { \
;     A_[i] = *(const u32x4*)((const char*)Ap + (aoff + (unsigned)(32 * i * lda + (kt) * 64) * 2u)); B_[i] = *(const u32x4*)((const char*)Wt + (woff + (unsigned)(32 * i * K + (kt) * 64) * 2u)); } } while (0)
; #define BLOAD(A_, B_, kt) do { _Pragma("unroll") for (int i = 0; i < 4; ++i) { \
;     A_[i] = *(const u32x4*)((const char*)Ap + (aoff + (unsigned)(32 * i * lda + (kt) * 64) * 2u)); B_[i] = *(const u32x4*)((const char*)Wt + (woff + (unsigned)(32 * i * K + (kt) * 64) * 2u)); } } while (0)
; #define BSTORE(A_, B_, buf) do { _Pragma("unroll") for (int i = 0; i < 4; ++i) { \
;     *(u32x4*)&As[(buf) * GBUF + (srow + 32 * i) * LDT + sc8] = A_[i]; \
;     *(u32x4*)&Bs[(buf) * GBUF + (srow + 32 * i) * LDT + sc8] = B_[i]; } } while (0)
; template <int NK>
; DI void gemm_run(PF& pf, const u16* __restrict__ Ap, int lda, const u16* __restrict__ Wt, f32x16 (&acc)[2][2], char* smem) {
;     ...
;   __builtin_amdgcn_s_setprio(0);
;   __syncthreads();
;   BSTORE(pf.a0, pf.b0, 0);
;   BLOAD(pf.a0, pf.b0, 2);
;   __syncthreads();
; #pragma unroll
;   for (int kt = 0; kt < nk; kt += 2) {
;     BCOMP(0);
;     BSTORE(pf.a1, pf.b1, 1);
;     if (kt + 3 < nk) BLOAD(pf.a1, pf.b1, kt + 3);
;     __syncthreads();
;     BCOMP(1);
;     if (kt + 2 < nk) { BSTORE(pf.a0, pf.b0, 0); if (kt + 4 < nk) BLOAD(pf.a0, pf.b0, kt + 4); }
;     __syncthreads();
;   }
	ds_read_b128 v[208:211], v138 offset:0
	ds_read_b128 v[224:227], v140 offset:0
	ds_read_b128 v[228:231], v140 offset:1024
	ds_read_b128 v[232:235], v140 offset:2048
	ds_read_b128 v[236:239], v140 offset:3072
	ds_read_b128 v[212:215], v138 offset:1024
	s_waitcnt lgkmcnt(4)
	v_mfma_f32_16x16x32_bf16 v[2:5], v[224:227], v[208:211], v[2:5]
	ds_read_b128 v[216:219], v138 offset:2048
	s_waitcnt lgkmcnt(4)
	v_mfma_f32_16x16x32_bf16 v[6:9], v[228:231], v[208:211], v[6:9]
	ds_read_b128 v[220:223], v138 offset:3072
	s_waitcnt lgkmcnt(4)
	v_mfma_f32_16x16x32_bf16 v[10:13], v[232:235], v[208:211], v[10:13]
	s_waitcnt lgkmcnt(3)
	v_mfma_f32_16x16x32_bf16 v[14:17], v[236:239], v[208:211], v[14:17]
	s_waitcnt lgkmcnt(2)
	v_mfma_f32_16x16x32_bf16 v[18:21], v[224:227], v[212:215], v[18:21]
	ds_read_b128 v[240:243], v140 offset:8192
	v_mfma_f32_16x16x32_bf16 v[22:25], v[228:231], v[212:215], v[22:25]
	ds_read_b128 v[244:247], v140 offset:9216
	v_mfma_f32_16x16x32_bf16 v[26:29], v[232:235], v[212:215], v[26:29]
	ds_read_b128 v[248:251], v140 offset:10240
	v_mfma_f32_16x16x32_bf16 v[30:33], v[236:239], v[212:215], v[30:33]
	ds_read_b128 v[156:159], v140 offset:11264
	s_waitcnt lgkmcnt(5)
	v_mfma_f32_16x16x32_bf16 v[34:37], v[224:227], v[216:219], v[34:37]
	v_mfma_f32_16x16x32_bf16 v[38:41], v[228:231], v[216:219], v[38:41]
	v_mfma_f32_16x16x32_bf16 v[42:45], v[232:235], v[216:219], v[42:45]
	v_mfma_f32_16x16x32_bf16 v[46:49], v[236:239], v[216:219], v[46:49]
	s_waitcnt lgkmcnt(4)
	v_mfma_f32_16x16x32_bf16 v[50:53], v[224:227], v[220:223], v[50:53]
	v_mfma_f32_16x16x32_bf16 v[54:57], v[228:231], v[220:223], v[54:57]
	v_mfma_f32_16x16x32_bf16 v[58:61], v[232:235], v[220:223], v[58:61]
	v_mfma_f32_16x16x32_bf16 v[62:65], v[236:239], v[220:223], v[62:65]
	s_waitcnt lgkmcnt(3)
	v_mfma_f32_16x16x32_bf16 v[74:77], v[240:243], v[208:211], v[74:77]
	s_waitcnt lgkmcnt(2)
	v_mfma_f32_16x16x32_bf16 v[78:81], v[244:247], v[208:211], v[78:81]
	s_waitcnt lgkmcnt(1)
	v_mfma_f32_16x16x32_bf16 v[82:85], v[248:251], v[208:211], v[82:85]
	s_waitcnt lgkmcnt(0)
	v_mfma_f32_16x16x32_bf16 v[86:89], v[156:159], v[208:211], v[86:89]
	v_mfma_f32_16x16x32_bf16 v[90:93], v[240:243], v[212:215], v[90:93]
	v_mfma_f32_16x16x32_bf16 v[94:97], v[244:247], v[212:215], v[94:97]
	v_mfma_f32_16x16x32_bf16 v[98:101], v[248:251], v[212:215], v[98:101]
	v_mfma_f32_16x16x32_bf16 v[102:105], v[156:159], v[212:215], v[102:105]
	v_mfma_f32_16x16x32_bf16 v[106:109], v[240:243], v[216:219], v[106:109]
	v_mfma_f32_16x16x32_bf16 v[110:113], v[244:247], v[216:219], v[110:113]
	v_mfma_f32_16x16x32_bf16 v[114:117], v[248:251], v[216:219], v[114:117]
	v_mfma_f32_16x16x32_bf16 v[118:121], v[156:159], v[216:219], v[118:121]
	v_mfma_f32_16x16x32_bf16 v[122:125], v[240:243], v[220:223], v[122:125]
	v_mfma_f32_16x16x32_bf16 v[126:129], v[244:247], v[220:223], v[126:129]
	v_mfma_f32_16x16x32_bf16 v[130:133], v[248:251], v[220:223], v[130:133]
	v_mfma_f32_16x16x32_bf16 v[134:137], v[156:159], v[220:223], v[134:137]
	s_waitcnt vmcnt(0)
	s_barrier
	ds_read_b128 v[208:211], v138 offset:24576
	ds_read_b128 v[224:227], v140 offset:24576
	ds_read_b128 v[228:231], v140 offset:25600
	ds_read_b128 v[232:235], v140 offset:26624
	ds_read_b128 v[236:239], v140 offset:27648
	ds_read_b128 v[212:215], v138 offset:25600
	s_waitcnt lgkmcnt(4)
	v_mfma_f32_16x16x32_bf16 v[2:5], v[224:227], v[208:211], v[2:5]
	ds_read_b128 v[216:219], v138 offset:26624
	s_waitcnt lgkmcnt(4)
	v_mfma_f32_16x16x32_bf16 v[6:9], v[228:231], v[208:211], v[6:9]
	ds_read_b128 v[220:223], v138 offset:27648
	s_waitcnt lgkmcnt(4)
	v_mfma_f32_16x16x32_bf16 v[10:13], v[232:235], v[208:211], v[10:13]
	s_waitcnt lgkmcnt(3)
	v_mfma_f32_16x16x32_bf16 v[14:17], v[236:239], v[208:211], v[14:17]
	s_waitcnt lgkmcnt(2)
	v_mfma_f32_16x16x32_bf16 v[18:21], v[224:227], v[212:215], v[18:21]
	ds_read_b128 v[240:243], v140 offset:32768
	v_mfma_f32_16x16x32_bf16 v[22:25], v[228:231], v[212:215], v[22:25]
	ds_read_b128 v[244:247], v140 offset:33792
	v_mfma_f32_16x16x32_bf16 v[26:29], v[232:235], v[212:215], v[26:29]
	ds_read_b128 v[248:251], v140 offset:34816
	v_mfma_f32_16x16x32_bf16 v[30:33], v[236:239], v[212:215], v[30:33]
	ds_read_b128 v[156:159], v140 offset:35840
	s_waitcnt lgkmcnt(5)
	v_mfma_f32_16x16x32_bf16 v[34:37], v[224:227], v[216:219], v[34:37]
	v_mfma_f32_16x16x32_bf16 v[38:41], v[228:231], v[216:219], v[38:41]
	v_mfma_f32_16x16x32_bf16 v[42:45], v[232:235], v[216:219], v[42:45]
	v_mfma_f32_16x16x32_bf16 v[46:49], v[236:239], v[216:219], v[46:49]
	s_waitcnt lgkmcnt(4)
	v_mfma_f32_16x16x32_bf16 v[50:53], v[224:227], v[220:223], v[50:53]
	v_mfma_f32_16x16x32_bf16 v[54:57], v[228:231], v[220:223], v[54:57]
	v_mfma_f32_16x16x32_bf16 v[58:61], v[232:235], v[220:223], v[58:61]
	v_mfma_f32_16x16x32_bf16 v[62:65], v[236:239], v[220:223], v[62:65]
	s_waitcnt lgkmcnt(3)
	v_mfma_f32_16x16x32_bf16 v[74:77], v[240:243], v[208:211], v[74:77]
	s_waitcnt lgkmcnt(2)
	v_mfma_f32_16x16x32_bf16 v[78:81], v[244:247], v[208:211], v[78:81]
	s_waitcnt lgkmcnt(1)
	v_mfma_f32_16x16x32_bf16 v[82:85], v[248:251], v[208:211], v[82:85]
	s_waitcnt lgkmcnt(0)
	v_mfma_f32_16x16x32_bf16 v[86:89], v[156:159], v[208:211], v[86:89]
	v_mfma_f32_16x16x32_bf16 v[90:93], v[240:243], v[212:215], v[90:93]
	v_mfma_f32_16x16x32_bf16 v[94:97], v[244:247], v[212:215], v[94:97]
	v_mfma_f32_16x16x32_bf16 v[98:101], v[248:251], v[212:215], v[98:101]
	v_mfma_f32_16x16x32_bf16 v[102:105], v[156:159], v[212:215], v[102:105]
	v_mfma_f32_16x16x32_bf16 v[106:109], v[240:243], v[216:219], v[106:109]
	v_mfma_f32_16x16x32_bf16 v[110:113], v[244:247], v[216:219], v[110:113]
	v_mfma_f32_16x16x32_bf16 v[114:117], v[248:251], v[216:219], v[114:117]
	v_mfma_f32_16x16x32_bf16 v[118:121], v[156:159], v[216:219], v[118:121]
	v_mfma_f32_16x16x32_bf16 v[122:125], v[240:243], v[220:223], v[122:125]
	v_mfma_f32_16x16x32_bf16 v[126:129], v[244:247], v[220:223], v[126:129]
	v_mfma_f32_16x16x32_bf16 v[130:133], v[248:251], v[220:223], v[130:133]
	v_mfma_f32_16x16x32_bf16 v[134:137], v[156:159], v[220:223], v[134:137]
	s_barrier

; #define BLOAD(A_, B_, kt) do { _Pragma("unroll") for (int i = 0; i < 4; ++i) { \
;     A_[i] = *(const u32x4*)((const char*)Ap + (aoff + (unsigned)(32 * i * lda + (kt) * 64) * 2u)); B_[i] = *(const u32x4*)((const char*)Wt + (woff + (unsigned)(32 * i * K + (kt) * 64) * 2u)); } } while (0)
; #define BLOAD(A_, B_, kt) do { _Pragma("unroll") for (int i = 0; i < 4; ++i) { \
;     A_[i] = *(const u32x4*)((const char*)Ap + (aoff + (unsigned)(32 * i * lda + (kt) * 64) * 2u)); B_[i] = *(const u32x4*)((const char*)Wt + (woff + (unsigned)(32 * i * K + (kt) * 64) * 2u)); } } while (0)
; #define BSTORE(A_, B_, buf) do { _Pragma("unroll") for (int i = 0; i < 4; ++i) { \
;     *(u32x4*)&As[(buf) * GBUF + (srow + 32 * i) * LDT + sc8] = A_[i]; \
;     *(u32x4*)&Bs[(buf) * GBUF + (srow + 32 * i) * LDT + sc8] = B_[i]; } } while (0)
; template <int NK>
; DI void gemm_run(PF& pf, const u16* __restrict__ Ap, int lda, const u16* __restrict__ Wt, f32x16 (&acc)[2][2], char* smem) {
;     ...
;   __builtin_amdgcn_s_setprio(0);
;   __syncthreads();
;   BSTORE(pf.a0, pf.b0, 0);
;   BLOAD(pf.a0, pf.b0, 2);
;   __syncthreads();
; #pragma unroll
;   for (int kt = 0; kt < nk; kt += 2) {
;     BCOMP(0);
;     BSTORE(pf.a1, pf.b1, 1);
;     if (kt + 3 < nk) BLOAD(pf.a1, pf.b1, kt + 3);
;     __syncthreads();
;     BCOMP(1);
;     if (kt + 2 < nk) { BSTORE(pf.a0, pf.b0, 0); if (kt + 4 < nk) BLOAD(pf.a0, pf.b0, kt + 4); }
;     __syncthreads();
;   }
.Lout_kloop:
	s_waitcnt vmcnt(6)
	s_barrier
	ds_read_b128 v[224:227], v126 offset:0
	ds_read_b128 v[240:243], v128 offset:0
	ds_read_b128 v[244:247], v128 offset:1024
	ds_read_b128 v[248:251], v128 offset:2048
	ds_read_b128 v[156:159], v128 offset:3072
	ds_read_b128 v[228:231], v126 offset:1024
	s_waitcnt lgkmcnt(4)
	v_mfma_f32_16x16x32_bf16 v[2:5], v[240:243], v[224:227], v[2:5]
	ds_read_b128 v[232:235], v126 offset:2048
	s_waitcnt lgkmcnt(4)
	v_mfma_f32_16x16x32_bf16 v[6:9], v[244:247], v[224:227], v[6:9]
	ds_read_b128 v[236:239], v126 offset:3072
	s_waitcnt lgkmcnt(4)
	v_mfma_f32_16x16x32_bf16 v[10:13], v[248:251], v[224:227], v[10:13]
	s_add_u32 m0, s42, 0xc000
	s_add_u32 s28, s28, 0x100000
	s_addc_u32 s29, s29, 0
	global_load_lds_dwordx4 v143, s[28:29]
	global_load_lds_dwordx4 v144, s[28:29] offset:1024
	s_add_u32 m0, s43, 0xc000
	s_add_u32 s30, s30, 0x10000
	s_addc_u32 s31, s31, 0
	global_load_lds_dwordx4 v145, s[30:31]
	global_load_lds_dwordx4 v146, s[30:31] offset:1024
	global_load_lds_dwordx4 v147, s[30:31] offset:2048
	global_load_lds_dwordx4 v148, s[30:31] offset:3072
	s_waitcnt lgkmcnt(3)
	v_mfma_f32_16x16x32_bf16 v[14:17], v[156:159], v[224:227], v[14:17]
	s_waitcnt lgkmcnt(2)
	v_mfma_f32_16x16x32_bf16 v[18:21], v[240:243], v[228:231], v[18:21]
	ds_read_b128 v[160:163], v128 offset:8192
	v_mfma_f32_16x16x32_bf16 v[22:25], v[244:247], v[228:231], v[22:25]
	ds_read_b128 v[164:167], v128 offset:9216
	v_mfma_f32_16x16x32_bf16 v[26:29], v[248:251], v[228:231], v[26:29]
	ds_read_b128 v[168:171], v128 offset:10240
	v_mfma_f32_16x16x32_bf16 v[30:33], v[156:159], v[228:231], v[30:33]
	ds_read_b128 v[122:125], v128 offset:11264
	s_waitcnt lgkmcnt(5)
	v_mfma_f32_16x16x32_bf16 v[34:37], v[240:243], v[232:235], v[34:37]
	v_mfma_f32_16x16x32_bf16 v[38:41], v[244:247], v[232:235], v[38:41]
	v_mfma_f32_16x16x32_bf16 v[42:45], v[248:251], v[232:235], v[42:45]
	v_mfma_f32_16x16x32_bf16 v[46:49], v[156:159], v[232:235], v[46:49]
	s_waitcnt lgkmcnt(4)
	v_mfma_f32_16x16x32_bf16 v[50:53], v[240:243], v[236:239], v[50:53]
	v_mfma_f32_16x16x32_bf16 v[54:57], v[244:247], v[236:239], v[54:57]
	v_mfma_f32_16x16x32_bf16 v[58:61], v[248:251], v[236:239], v[58:61]
	v_mfma_f32_16x16x32_bf16 v[62:65], v[156:159], v[236:239], v[62:65]
	s_waitcnt lgkmcnt(3)
	v_mfma_f32_16x16x32_bf16 v[74:77], v[160:163], v[224:227], v[74:77]
	s_waitcnt lgkmcnt(2)
	v_mfma_f32_16x16x32_bf16 v[78:81], v[164:167], v[224:227], v[78:81]
	s_waitcnt lgkmcnt(1)
	v_mfma_f32_16x16x32_bf16 v[82:85], v[168:171], v[224:227], v[82:85]
	s_waitcnt lgkmcnt(0)
	v_mfma_f32_16x16x32_bf16 v[86:89], v[122:125], v[224:227], v[86:89]
	v_mfma_f32_16x16x32_bf16 v[90:93], v[160:163], v[228:231], v[90:93]
	v_mfma_f32_16x16x32_bf16 v[94:97], v[164:167], v[228:231], v[94:97]
	v_mfma_f32_16x16x32_bf16 v[98:101], v[168:171], v[228:231], v[98:101]
	v_mfma_f32_16x16x32_bf16 v[102:105], v[122:125], v[228:231], v[102:105]
	v_mfma_f32_16x16x32_bf16 v[106:109], v[160:163], v[232:235], v[106:109]
	v_mfma_f32_16x16x32_bf16 v[110:113], v[164:167], v[232:235], v[110:113]
	v_mfma_f32_16x16x32_bf16 v[114:117], v[168:171], v[232:235], v[114:117]
	v_mfma_f32_16x16x32_bf16 v[118:121], v[122:125], v[232:235], v[118:121]
	v_mfma_f32_16x16x32_bf16 v[208:211], v[160:163], v[236:239], v[208:211]
	v_mfma_f32_16x16x32_bf16 v[212:215], v[164:167], v[236:239], v[212:215]
	v_mfma_f32_16x16x32_bf16 v[216:219], v[168:171], v[236:239], v[216:219]
	v_mfma_f32_16x16x32_bf16 v[220:223], v[122:125], v[236:239], v[220:223]
	s_waitcnt vmcnt(6)
	s_barrier
	ds_read_b128 v[224:227], v126 offset:24576
	ds_read_b128 v[240:243], v128 offset:24576
	ds_read_b128 v[244:247], v128 offset:25600
	ds_read_b128 v[248:251], v128 offset:26624
	ds_read_b128 v[156:159], v128 offset:27648
	ds_read_b128 v[228:231], v126 offset:25600
	s_waitcnt lgkmcnt(4)
	v_mfma_f32_16x16x32_bf16 v[2:5], v[240:243], v[224:227], v[2:5]
	ds_read_b128 v[232:235], v126 offset:26624
	s_waitcnt lgkmcnt(4)
	v_mfma_f32_16x16x32_bf16 v[6:9], v[244:247], v[224:227], v[6:9]
	ds_read_b128 v[236:239], v126 offset:27648
	s_waitcnt lgkmcnt(4)
	v_mfma_f32_16x16x32_bf16 v[10:13], v[248:251], v[224:227], v[10:13]
	s_add_u32 m0, s42, 0x0
	s_add_u32 s28, s28, 0x100000
	s_addc_u32 s29, s29, 0
	global_load_lds_dwordx4 v143, s[28:29]
	global_load_lds_dwordx4 v144, s[28:29] offset:1024
	s_add_u32 m0, s43, 0x0
	s_add_u32 s30, s30, 0x10000
	s_addc_u32 s31, s31, 0
	global_load_lds_dwordx4 v145, s[30:31]
	global_load_lds_dwordx4 v146, s[30:31] offset:1024
	global_load_lds_dwordx4 v147, s[30:31] offset:2048
	global_load_lds_dwordx4 v148, s[30:31] offset:3072
	s_waitcnt lgkmcnt(3)
	v_mfma_f32_16x16x32_bf16 v[14:17], v[156:159], v[224:227], v[14:17]
	s_waitcnt lgkmcnt(2)
	v_mfma_f32_16x16x32_bf16 v[18:21], v[240:243], v[228:231], v[18:21]
	ds_read_b128 v[160:163], v128 offset:32768
	v_mfma_f32_16x16x32_bf16 v[22:25], v[244:247], v[228:231], v[22:25]
	ds_read_b128 v[164:167], v128 offset:33792
	v_mfma_f32_16x16x32_bf16 v[26:29], v[248:251], v[228:231], v[26:29]
	ds_read_b128 v[168:171], v128 offset:34816
	v_mfma_f32_16x16x32_bf16 v[30:33], v[156:159], v[228:231], v[30:33]
	ds_read_b128 v[122:125], v128 offset:35840
	s_waitcnt lgkmcnt(5)
	v_mfma_f32_16x16x32_bf16 v[34:37], v[240:243], v[232:235], v[34:37]
	v_mfma_f32_16x16x32_bf16 v[38:41], v[244:247], v[232:235], v[38:41]
	v_mfma_f32_16x16x32_bf16 v[42:45], v[248:251], v[232:235], v[42:45]
	v_mfma_f32_16x16x32_bf16 v[46:49], v[156:159], v[232:235], v[46:49]
	s_waitcnt lgkmcnt(4)
	v_mfma_f32_16x16x32_bf16 v[50:53], v[240:243], v[236:239], v[50:53]
	v_mfma_f32_16x16x32_bf16 v[54:57], v[244:247], v[236:239], v[54:57]
	v_mfma_f32_16x16x32_bf16 v[58:61], v[248:251], v[236:239], v[58:61]
	v_mfma_f32_16x16x32_bf16 v[62:65], v[156:159], v[236:239], v[62:65]
	s_waitcnt lgkmcnt(3)
	v_mfma_f32_16x16x32_bf16 v[74:77], v[160:163], v[224:227], v[74:77]
	s_waitcnt lgkmcnt(2)
	v_mfma_f32_16x16x32_bf16 v[78:81], v[164:167], v[224:227], v[78:81]
	s_waitcnt lgkmcnt(1)
	v_mfma_f32_16x16x32_bf16 v[82:85], v[168:171], v[224:227], v[82:85]
	s_waitcnt lgkmcnt(0)
	v_mfma_f32_16x16x32_bf16 v[86:89], v[122:125], v[224:227], v[86:89]
	v_mfma_f32_16x16x32_bf16 v[90:93], v[160:163], v[228:231], v[90:93]
	v_mfma_f32_16x16x32_bf16 v[94:97], v[164:167], v[228:231], v[94:97]
	v_mfma_f32_16x16x32_bf16 v[98:101], v[168:171], v[228:231], v[98:101]
	v_mfma_f32_16x16x32_bf16 v[102:105], v[122:125], v[228:231], v[102:105]
	v_mfma_f32_16x16x32_bf16 v[106:109], v[160:163], v[232:235], v[106:109]
	v_mfma_f32_16x16x32_bf16 v[110:113], v[164:167], v[232:235], v[110:113]
	v_mfma_f32_16x16x32_bf16 v[114:117], v[168:171], v[232:235], v[114:117]
	v_mfma_f32_16x16x32_bf16 v[118:121], v[122:125], v[232:235], v[118:121]
	v_mfma_f32_16x16x32_bf16 v[208:211], v[160:163], v[236:239], v[208:211]
	v_mfma_f32_16x16x32_bf16 v[212:215], v[164:167], v[236:239], v[212:215]
	v_mfma_f32_16x16x32_bf16 v[216:219], v[168:171], v[236:239], v[216:219]
	v_mfma_f32_16x16x32_bf16 v[220:223], v[122:125], v[236:239], v[220:223]
	s_waitcnt vmcnt(6)
	s_barrier
; #define BLOAD(A_, B_, kt) do { _Pragma("unroll") for (int i = 0; i < 4; ++i) { \
;     A_[i] = *(const u32x4*)((const char*)Ap + (aoff + (unsigned)(32 * i * lda + (kt) * 64) * 2u)); B_[i] = *(const u32x4*)((const char*)Wt + (woff + (unsigned)(32 * i * K + (kt) * 64) * 2u)); } } while (0)
; #define BLOAD(A_, B_, kt) do { _Pragma("unroll") for (int i = 0; i < 4; ++i) { \
;     A_[i] = *(const u32x4*)((const char*)Ap + (aoff + (unsigned)(32 * i * lda + (kt) * 64) * 2u)); B_[i] = *(const u32x4*)((const char*)Wt + (woff + (unsigned)(32 * i * K + (kt) * 64) * 2u)); } } while (0)
; #define BSTORE(A_, B_, buf) do { _Pragma("unroll") for (int i = 0; i < 4; ++i) { \
;     *(u32x4*)&As[(buf) * GBUF + (srow + 32 * i) * LDT + sc8] = A_[i]; \
;     *(u32x4*)&Bs[(buf) * GBUF + (srow + 32 * i) * LDT + sc8] = B_[i]; } } while (0)
; template <int NK>
; DI void gemm_run(PF& pf, const u16* __restrict__ Ap, int lda, const u16* __restrict__ Wt, f32x16 (&acc)[2][2], char* smem) {
;     ...
;   __builtin_amdgcn_s_setprio(0);
;   __syncthreads();
;   BSTORE(pf.a0, pf.b0, 0);
;   BLOAD(pf.a0, pf.b0, 2);
;   __syncthreads();
; #pragma unroll
;   for (int kt = 0; kt < nk; kt += 2) {
;     BCOMP(0);
;     BSTORE(pf.a1, pf.b1, 1);
;     if (kt + 3 < nk) BLOAD(pf.a1, pf.b1, kt + 3);
;     __syncthreads();
;     BCOMP(1);
;     if (kt + 2 < nk) { BSTORE(pf.a0, pf.b0, 0); if (kt + 4 < nk) BLOAD(pf.a0, pf.b0, kt + 4); }
;     __syncthreads();
;   }
	ds_read_b128 v[224:227], v126 offset:49152
	ds_read_b128 v[240:243], v128 offset:49152
	ds_read_b128 v[244:247], v128 offset:50176
	ds_read_b128 v[248:251], v128 offset:51200
	ds_read_b128 v[156:159], v128 offset:52224
	ds_read_b128 v[228:231], v126 offset:50176
	s_waitcnt lgkmcnt(4)
	v_mfma_f32_16x16x32_bf16 v[2:5], v[240:243], v[224:227], v[2:5]
	ds_read_b128 v[232:235], v126 offset:51200
	s_waitcnt lgkmcnt(4)
	v_mfma_f32_16x16x32_bf16 v[6:9], v[244:247], v[224:227], v[6:9]
	ds_read_b128 v[236:239], v126 offset:52224
	s_waitcnt lgkmcnt(4)
	v_mfma_f32_16x16x32_bf16 v[10:13], v[248:251], v[224:227], v[10:13]
	s_add_u32 m0, s42, 0x6000
	s_add_u32 s28, s28, 0x100000
	s_addc_u32 s29, s29, 0
	global_load_lds_dwordx4 v143, s[28:29]
	global_load_lds_dwordx4 v144, s[28:29] offset:1024
	s_add_u32 m0, s43, 0x6000
	s_add_u32 s30, s30, 0x10000
	s_addc_u32 s31, s31, 0
	global_load_lds_dwordx4 v145, s[30:31]
	global_load_lds_dwordx4 v146, s[30:31] offset:1024
	global_load_lds_dwordx4 v147, s[30:31] offset:2048
	global_load_lds_dwordx4 v148, s[30:31] offset:3072
	s_waitcnt lgkmcnt(3)
	v_mfma_f32_16x16x32_bf16 v[14:17], v[156:159], v[224:227], v[14:17]
	s_waitcnt lgkmcnt(2)
	v_mfma_f32_16x16x32_bf16 v[18:21], v[240:243], v[228:231], v[18:21]
	ds_read_b128 v[160:163], v128 offset:57344
	v_mfma_f32_16x16x32_bf16 v[22:25], v[244:247], v[228:231], v[22:25]
	ds_read_b128 v[164:167], v128 offset:58368
	v_mfma_f32_16x16x32_bf16 v[26:29], v[248:251], v[228:231], v[26:29]
	ds_read_b128 v[168:171], v128 offset:59392
	v_mfma_f32_16x16x32_bf16 v[30:33], v[156:159], v[228:231], v[30:33]
	ds_read_b128 v[122:125], v128 offset:60416
	s_waitcnt lgkmcnt(5)
	v_mfma_f32_16x16x32_bf16 v[34:37], v[240:243], v[232:235], v[34:37]
	v_mfma_f32_16x16x32_bf16 v[38:41], v[244:247], v[232:235], v[38:41]
	v_mfma_f32_16x16x32_bf16 v[42:45], v[248:251], v[232:235], v[42:45]
	v_mfma_f32_16x16x32_bf16 v[46:49], v[156:159], v[232:235], v[46:49]
	s_waitcnt lgkmcnt(4)
	v_mfma_f32_16x16x32_bf16 v[50:53], v[240:243], v[236:239], v[50:53]
	v_mfma_f32_16x16x32_bf16 v[54:57], v[244:247], v[236:239], v[54:57]
	v_mfma_f32_16x16x32_bf16 v[58:61], v[248:251], v[236:239], v[58:61]
	v_mfma_f32_16x16x32_bf16 v[62:65], v[156:159], v[236:239], v[62:65]
	s_waitcnt lgkmcnt(3)
	v_mfma_f32_16x16x32_bf16 v[74:77], v[160:163], v[224:227], v[74:77]
	s_waitcnt lgkmcnt(2)
	v_mfma_f32_16x16x32_bf16 v[78:81], v[164:167], v[224:227], v[78:81]
	s_waitcnt lgkmcnt(1)
	v_mfma_f32_16x16x32_bf16 v[82:85], v[168:171], v[224:227], v[82:85]
	s_waitcnt lgkmcnt(0)
	v_mfma_f32_16x16x32_bf16 v[86:89], v[122:125], v[224:227], v[86:89]
	v_mfma_f32_16x16x32_bf16 v[90:93], v[160:163], v[228:231], v[90:93]
	v_mfma_f32_16x16x32_bf16 v[94:97], v[164:167], v[228:231], v[94:97]
	v_mfma_f32_16x16x32_bf16 v[98:101], v[168:171], v[228:231], v[98:101]
	v_mfma_f32_16x16x32_bf16 v[102:105], v[122:125], v[228:231], v[102:105]
	v_mfma_f32_16x16x32_bf16 v[106:109], v[160:163], v[232:235], v[106:109]
	v_mfma_f32_16x16x32_bf16 v[110:113], v[164:167], v[232:235], v[110:113]
	v_mfma_f32_16x16x32_bf16 v[114:117], v[168:171], v[232:235], v[114:117]
	v_mfma_f32_16x16x32_bf16 v[118:121], v[122:125], v[232:235], v[118:121]
	v_mfma_f32_16x16x32_bf16 v[208:211], v[160:163], v[236:239], v[208:211]
	v_mfma_f32_16x16x32_bf16 v[212:215], v[164:167], v[236:239], v[212:215]
	v_mfma_f32_16x16x32_bf16 v[216:219], v[168:171], v[236:239], v[216:219]
	v_mfma_f32_16x16x32_bf16 v[220:223], v[122:125], v[236:239], v[220:223]
	s_sub_u32 s46, s46, 1
	s_cmp_lg_u32 s46, 0
	s_cbranch_scc1 .Lout_kloop
	s_waitcnt vmcnt(6)
	s_barrier
	ds_read_b128 v[224:227], v126 offset:0
	ds_read_b128 v[240:243], v128 offset:0
	ds_read_b128 v[244:247], v128 offset:1024
	ds_read_b128 v[248:251], v128 offset:2048
	ds_read_b128 v[156:159], v128 offset:3072
	ds_read_b128 v[228:231], v126 offset:1024
	s_waitcnt lgkmcnt(4)
	v_mfma_f32_16x16x32_bf16 v[2:5], v[240:243], v[224:227], v[2:5]
	ds_read_b128 v[232:235], v126 offset:2048
	s_waitcnt lgkmcnt(4)
	v_mfma_f32_16x16x32_bf16 v[6:9], v[244:247], v[224:227], v[6:9]
	ds_read_b128 v[236:239], v126 offset:3072
	s_waitcnt lgkmcnt(4)
	v_mfma_f32_16x16x32_bf16 v[10:13], v[248:251], v[224:227], v[10:13]
	s_waitcnt lgkmcnt(3)
	v_mfma_f32_16x16x32_bf16 v[14:17], v[156:159], v[224:227], v[14:17]
	s_waitcnt lgkmcnt(2)
	v_mfma_f32_16x16x32_bf16 v[18:21], v[240:243], v[228:231], v[18:21]
	ds_read_b128 v[160:163], v128 offset:8192
	v_mfma_f32_16x16x32_bf16 v[22:25], v[244:247], v[228:231], v[22:25]
	ds_read_b128 v[164:167], v128 offset:9216
	v_mfma_f32_16x16x32_bf16 v[26:29], v[248:251], v[228:231], v[26:29]
	ds_read_b128 v[168:171], v128 offset:10240
	v_mfma_f32_16x16x32_bf16 v[30:33], v[156:159], v[228:231], v[30:33]
	ds_read_b128 v[122:125], v128 offset:11264
	s_waitcnt lgkmcnt(5)
	v_mfma_f32_16x16x32_bf16 v[34:37], v[240:243], v[232:235], v[34:37]
	v_mfma_f32_16x16x32_bf16 v[38:41], v[244:247], v[232:235], v[38:41]
	v_mfma_f32_16x16x32_bf16 v[42:45], v[248:251], v[232:235], v[42:45]
	v_mfma_f32_16x16x32_bf16 v[46:49], v[156:159], v[232:235], v[46:49]
	s_waitcnt lgkmcnt(4)
	v_mfma_f32_16x16x32_bf16 v[50:53], v[240:243], v[236:239], v[50:53]
	v_mfma_f32_16x16x32_bf16 v[54:57], v[244:247], v[236:239], v[54:57]
	v_mfma_f32_16x16x32_bf16 v[58:61], v[248:251], v[236:239], v[58:61]
	v_mfma_f32_16x16x32_bf16 v[62:65], v[156:159], v[236:239], v[62:65]
	s_waitcnt lgkmcnt(3)
	v_mfma_f32_16x16x32_bf16 v[74:77], v[160:163], v[224:227], v[74:77]
	s_waitcnt lgkmcnt(2)
	v_mfma_f32_16x16x32_bf16 v[78:81], v[164:167], v[224:227], v[78:81]
	s_waitcnt lgkmcnt(1)
	v_mfma_f32_16x16x32_bf16 v[82:85], v[168:171], v[224:227], v[82:85]
	s_waitcnt lgkmcnt(0)
	v_mfma_f32_16x16x32_bf16 v[86:89], v[122:125], v[224:227], v[86:89]
	v_mfma_f32_16x16x32_bf16 v[90:93], v[160:163], v[228:231], v[90:93]
	v_mfma_f32_16x16x32_bf16 v[94:97], v[164:167], v[228:231], v[94:97]
	v_mfma_f32_16x16x32_bf16 v[98:101], v[168:171], v[228:231], v[98:101]
	v_mfma_f32_16x16x32_bf16 v[102:105], v[122:125], v[228:231], v[102:105]
	v_mfma_f32_16x16x32_bf16 v[106:109], v[160:163], v[232:235], v[106:109]
	v_mfma_f32_16x16x32_bf16 v[110:113], v[164:167], v[232:235], v[110:113]
	v_mfma_f32_16x16x32_bf16 v[114:117], v[168:171], v[232:235], v[114:117]
	v_mfma_f32_16x16x32_bf16 v[118:121], v[122:125], v[232:235], v[118:121]
	v_mfma_f32_16x16x32_bf16 v[208:211], v[160:163], v[236:239], v[208:211]
	v_mfma_f32_16x16x32_bf16 v[212:215], v[164:167], v[236:239], v[212:215]
	v_mfma_f32_16x16x32_bf16 v[216:219], v[168:171], v[236:239], v[216:219]
	v_mfma_f32_16x16x32_bf16 v[220:223], v[122:125], v[236:239], v[220:223]
	s_waitcnt vmcnt(0)
	s_barrier
; #define BLOAD(A_, B_, kt) do { _Pragma("unroll") for (int i = 0; i < 4; ++i) { \
;     A_[i] = *(const u32x4*)((const char*)Ap + (aoff + (unsigned)(32 * i * lda + (kt) * 64) * 2u)); B_[i] = *(const u32x4*)((const char*)Wt + (woff + (unsigned)(32 * i * K + (kt) * 64) * 2u)); } } while (0)
; #define BLOAD(A_, B_, kt) do { _Pragma("unroll") for (int i = 0; i < 4; ++i) { \
;     A_[i] = *(const u32x4*)((const char*)Ap + (aoff + (unsigned)(32 * i * lda + (kt) * 64) * 2u)); B_[i] = *(const u32x4*)((const char*)Wt + (woff + (unsigned)(32 * i * K + (kt) * 64) * 2u)); } } while (0)
; #define BSTORE(A_, B_, buf) do { _Pragma("unroll") for (int i = 0; i < 4; ++i) { \
;     *(u32x4*)&As[(buf) * GBUF + (srow + 32 * i) * LDT + sc8] = A_[i]; \
;     *(u32x4*)&Bs[(buf) * GBUF + (srow + 32 * i) * LDT + sc8] = B_[i]; } } while (0)
; template <int NK>
; DI void gemm_run(PF& pf, const u16* __restrict__ Ap, int lda, const u16* __restrict__ Wt, f32x16 (&acc)[2][2], char* smem) {
;     ...
; #pragma unroll
;   for (int kt = 0; kt < nk; kt += 2) {
;     BCOMP(0);
;     BSTORE(pf.a1, pf.b1, 1);
;     if (kt + 3 < nk) BLOAD(pf.a1, pf.b1, kt + 3);
;     __syncthreads();
;     BCOMP(1);
;     if (kt + 2 < nk) { BSTORE(pf.a0, pf.b0, 0); if (kt + 4 < nk) BLOAD(pf.a0, pf.b0, kt + 4); }
;     __syncthreads();
;   }
; DI void tile_outproj(const Params& p, int l, const Chunk& ck, int tile, int next, PF& pf, char* smem) {
;     ...
;   const int row = tid >> 1, half = tid & 1; float ssq = 0.f;
;   u16* xb = (u16*)(p.ws + OFF_XB) + (size_t)(m0 + row) * 1024 + n0 + half * 64;
; #pragma unroll
;   for (int c8 = 0; c8 < 8; ++c8) {
;     float v[8], x[8]; cs_ld8(Cs, row, half * 64 + c8 * 8, v); unpack8(*(const u32x4*)(xb + c8 * 8), x);
	ds_read_b128 v[224:227], v126 offset:24576
	ds_read_b128 v[240:243], v128 offset:24576
	ds_read_b128 v[244:247], v128 offset:25600
	ds_read_b128 v[248:251], v128 offset:26624
	ds_read_b128 v[156:159], v128 offset:27648
	ds_read_b128 v[228:231], v126 offset:25600
	s_waitcnt lgkmcnt(4)
	v_mfma_f32_16x16x32_bf16 v[2:5], v[240:243], v[224:227], v[2:5]
	ds_read_b128 v[232:235], v126 offset:26624
	s_waitcnt lgkmcnt(4)
	v_mfma_f32_16x16x32_bf16 v[6:9], v[244:247], v[224:227], v[6:9]
	ds_read_b128 v[236:239], v126 offset:27648
	s_waitcnt lgkmcnt(4)
	v_mfma_f32_16x16x32_bf16 v[10:13], v[248:251], v[224:227], v[10:13]
	s_waitcnt lgkmcnt(3)
	v_mfma_f32_16x16x32_bf16 v[14:17], v[156:159], v[224:227], v[14:17]
	s_waitcnt lgkmcnt(2)
	v_mfma_f32_16x16x32_bf16 v[18:21], v[240:243], v[228:231], v[18:21]
	ds_read_b128 v[160:163], v128 offset:32768
	v_mfma_f32_16x16x32_bf16 v[22:25], v[244:247], v[228:231], v[22:25]
	ds_read_b128 v[164:167], v128 offset:33792
	v_mfma_f32_16x16x32_bf16 v[26:29], v[248:251], v[228:231], v[26:29]
	ds_read_b128 v[168:171], v128 offset:34816
	v_mfma_f32_16x16x32_bf16 v[30:33], v[156:159], v[228:231], v[30:33]
	ds_read_b128 v[122:125], v128 offset:35840
	s_waitcnt lgkmcnt(5)
	v_mfma_f32_16x16x32_bf16 v[34:37], v[240:243], v[232:235], v[34:37]
	v_mfma_f32_16x16x32_bf16 v[38:41], v[244:247], v[232:235], v[38:41]
	v_mfma_f32_16x16x32_bf16 v[42:45], v[248:251], v[232:235], v[42:45]
	v_mfma_f32_16x16x32_bf16 v[46:49], v[156:159], v[232:235], v[46:49]
	s_waitcnt lgkmcnt(4)
	v_mfma_f32_16x16x32_bf16 v[50:53], v[240:243], v[236:239], v[50:53]
	v_mfma_f32_16x16x32_bf16 v[54:57], v[244:247], v[236:239], v[54:57]
	v_mfma_f32_16x16x32_bf16 v[58:61], v[248:251], v[236:239], v[58:61]
	v_mfma_f32_16x16x32_bf16 v[62:65], v[156:159], v[236:239], v[62:65]
	s_waitcnt lgkmcnt(3)
	v_mfma_f32_16x16x32_bf16 v[74:77], v[160:163], v[224:227], v[74:77]
	s_waitcnt lgkmcnt(2)
	v_mfma_f32_16x16x32_bf16 v[78:81], v[164:167], v[224:227], v[78:81]
	s_waitcnt lgkmcnt(1)
	v_mfma_f32_16x16x32_bf16 v[82:85], v[168:171], v[224:227], v[82:85]
	s_waitcnt lgkmcnt(0)
	v_mfma_f32_16x16x32_bf16 v[86:89], v[122:125], v[224:227], v[86:89]
	v_mfma_f32_16x16x32_bf16 v[90:93], v[160:163], v[228:231], v[90:93]
	v_mfma_f32_16x16x32_bf16 v[94:97], v[164:167], v[228:231], v[94:97]
	v_mfma_f32_16x16x32_bf16 v[98:101], v[168:171], v[228:231], v[98:101]
	v_mfma_f32_16x16x32_bf16 v[102:105], v[122:125], v[228:231], v[102:105]
	v_mfma_f32_16x16x32_bf16 v[106:109], v[160:163], v[232:235], v[106:109]
	v_mfma_f32_16x16x32_bf16 v[110:113], v[164:167], v[232:235], v[110:113]
	v_mfma_f32_16x16x32_bf16 v[114:117], v[168:171], v[232:235], v[114:117]
	v_mfma_f32_16x16x32_bf16 v[118:121], v[122:125], v[232:235], v[118:121]
	v_mfma_f32_16x16x32_bf16 v[208:211], v[160:163], v[236:239], v[208:211]
	v_mfma_f32_16x16x32_bf16 v[212:215], v[164:167], v[236:239], v[212:215]
	v_mfma_f32_16x16x32_bf16 v[216:219], v[168:171], v[236:239], v[216:219]
	v_mfma_f32_16x16x32_bf16 v[220:223], v[122:125], v[236:239], v[220:223]
	s_barrier
	s_and_b32 s0, s40, 0x3f80
	v_and_b32_e32 v160, 63, v172
	v_lshrrev_b32_e32 v161, 6, v172
	v_and_b32_e32 v162, 15, v160
	v_lshrrev_b32_e32 v163, 4, v160
	v_lshrrev_b32_e32 v167, 1, v161
	v_lshl_add_u32 v167, v167, 6, v162
	v_and_b32_e32 v168, 1, v161
	v_lshlrev_b32_e32 v169, 6, v168
	v_lshl_add_u32 v169, v163, 2, v169
	v_add_u32_e32 v169, s26, v169
	v_add_u32_e32 v170, s0, v167
	v_lshlrev_b32_e32 v164, 6, v170
	v_lshl_add_u32 v164, v163, 3, v164
	v_lshrrev_b32_e32 v122, 5, v169
	v_lshl_add_u32 v164, v122, 20, v164
	v_add_u32_e32 v122, 0x100000, v164
	v_lshlrev_b32_e32 v165, 12, v167
	v_lshl_add_u32 v165, v169, 2, v165
	v_lshlrev_b32_e32 v166, 6, v170
	v_lshl_add_u32 v166, v168, 2, v166
	s_lshr_b32 s0, s26, 4
	s_add_u32 s14, s22, s0
	s_addc_u32 s15, s23, 0
	global_load_dwordx2 v[224:225], v164, s[20:21] offset:0
	global_load_dwordx2 v[226:227], v164, s[20:21] offset:32
	global_load_dwordx2 v[228:229], v122, s[20:21] offset:0
	global_load_dwordx2 v[230:231], v122, s[20:21] offset:32
	global_load_dwordx2 v[232:233], v164, s[20:21] offset:1024
	global_load_dwordx2 v[234:235], v164, s[20:21] offset:1056
	global_load_dwordx2 v[236:237], v122, s[20:21] offset:1024
	global_load_dwordx2 v[238:239], v122, s[20:21] offset:1056
	global_load_dwordx2 v[240:241], v164, s[20:21] offset:2048
	global_load_dwordx2 v[242:243], v164, s[20:21] offset:2080
	global_load_dwordx2 v[244:245], v122, s[20:21] offset:2048
	global_load_dwordx2 v[246:247], v122, s[20:21] offset:2080
	global_load_dwordx2 v[248:249], v164, s[20:21] offset:3072
	global_load_dwordx2 v[250:251], v164, s[20:21] offset:3104
	global_load_dwordx2 v[156:157], v122, s[20:21] offset:3072
	global_load_dwordx2 v[158:159], v122, s[20:21] offset:3104
	s_waitcnt vmcnt(0)
; DI u32x4 pack8(const float (&v)[8]) { u32x4 r = {pk2(v[0], v[1]), pk2(v[2], v[3]), pk2(v[4], v[5]), pk2(v[6], v[7])}; return r; }
; DI void tile_outproj(const Params& p, int l, const Chunk& ck, int tile, int next, PF& pf, char* smem) {
;     ...
;   const int row = tid >> 1, half = tid & 1; float ssq = 0.f;
;   u16* xb = (u16*)(p.ws + OFF_XB) + (size_t)(m0 + row) * 1024 + n0 + half * 64;
; #pragma unroll
;   for (int c8 = 0; c8 < 8; ++c8) {
;     float v[8], x[8]; cs_ld8(Cs, row, half * 64 + c8 * 8, v); unpack8(*(const u32x4*)(xb + c8 * 8), x);
; #pragma unroll
;     for (int j = 0; j < 8; ++j) { v[j] += x[j]; ssq += v[j] * v[j]; }
;     *(u32x4*)(xb + c8 * 8) = pack8(v);
;   }
;   ((float*)(p.ws + OFF_PSMID))[(size_t)(m0 + row) * 16 + ni * 2 + half] = ssq;
	v_mov_b32_e32 v171, 0
	v_lshlrev_b32_e32 v167, 16, v224
	v_and_b32_e32 v168, 0xffff0000, v224
	v_lshlrev_b32_e32 v169, 16, v225
	v_and_b32_e32 v170, 0xffff0000, v225
	v_add_f32_e32 v2, v2, v167
	v_add_f32_e32 v3, v3, v168
	v_add_f32_e32 v4, v4, v169
	v_add_f32_e32 v5, v5, v170
	v_fma_f32 v171, v2, v2, v171
	v_fma_f32 v171, v3, v3, v171
	v_fma_f32 v171, v4, v4, v171
	v_fma_f32 v171, v5, v5, v171
	v_cvt_pk_bf16_f32 v2, v2, v3
	v_cvt_pk_bf16_f32 v3, v4, v5
	global_store_dwordx2 v164, v[2:3], s[20:21]
	v_lshlrev_b32_e32 v167, 16, v226
	v_and_b32_e32 v168, 0xffff0000, v226
	v_lshlrev_b32_e32 v169, 16, v227
	v_and_b32_e32 v170, 0xffff0000, v227
	v_add_f32_e32 v6, v6, v167
	v_add_f32_e32 v7, v7, v168
	v_add_f32_e32 v8, v8, v169
	v_add_f32_e32 v9, v9, v170
	v_fma_f32 v171, v6, v6, v171
	v_fma_f32 v171, v7, v7, v171
	v_fma_f32 v171, v8, v8, v171
	v_fma_f32 v171, v9, v9, v171
	v_cvt_pk_bf16_f32 v6, v6, v7
	v_cvt_pk_bf16_f32 v7, v8, v9
	global_store_dwordx2 v164, v[6:7], s[20:21] offset:32
	v_lshlrev_b32_e32 v167, 16, v228
	v_and_b32_e32 v168, 0xffff0000, v228
	v_lshlrev_b32_e32 v169, 16, v229
	v_and_b32_e32 v170, 0xffff0000, v229
	v_add_f32_e32 v10, v10, v167
	v_add_f32_e32 v11, v11, v168
	v_add_f32_e32 v12, v12, v169
	v_add_f32_e32 v13, v13, v170
	v_fma_f32 v171, v10, v10, v171
	v_fma_f32 v171, v11, v11, v171
	v_fma_f32 v171, v12, v12, v171
	v_fma_f32 v171, v13, v13, v171
	v_cvt_pk_bf16_f32 v10, v10, v11
	v_cvt_pk_bf16_f32 v11, v12, v13
	global_store_dwordx2 v122, v[10:11], s[20:21]
	v_lshlrev_b32_e32 v167, 16, v230
	v_and_b32_e32 v168, 0xffff0000, v230
	v_lshlrev_b32_e32 v169, 16, v231
	v_and_b32_e32 v170, 0xffff0000, v231
	v_add_f32_e32 v14, v14, v167
	v_add_f32_e32 v15, v15, v168
	v_add_f32_e32 v16, v16, v169
	v_add_f32_e32 v17, v17, v170
	v_fma_f32 v171, v14, v14, v171
	v_fma_f32 v171, v15, v15, v171
	v_fma_f32 v171, v16, v16, v171
	v_fma_f32 v171, v17, v17, v171
	v_cvt_pk_bf16_f32 v14, v14, v15
	v_cvt_pk_bf16_f32 v15, v16, v17
	global_store_dwordx2 v122, v[14:15], s[20:21] offset:32
	v_mov_b32_e32 v167, v171
	s_nop 1
	v_permlane32_swap_b32_e32 v171, v167
	v_add_f32_e32 v171, v171, v167
	ds_swizzle_b32 v167, v171 offset:0x401f
	s_waitcnt lgkmcnt(0)
	v_add_f32_e32 v171, v171, v167
	v_cmp_gt_u32_e32 vcc, 16, v160
	s_and_saveexec_b64 s[98:99], vcc
	global_store_dword v166, v171, s[14:15] offset:0
	s_or_b64 exec, exec, s[98:99]
	v_mov_b32_e32 v171, 0
	v_lshlrev_b32_e32 v167, 16, v232
	v_and_b32_e32 v168, 0xffff0000, v232
	v_lshlrev_b32_e32 v169, 16, v233
	v_and_b32_e32 v170, 0xffff0000, v233
	v_add_f32_e32 v18, v18, v167
	v_add_f32_e32 v19, v19, v168
	v_add_f32_e32 v20, v20, v169
	v_add_f32_e32 v21, v21, v170
	v_fma_f32 v171, v18, v18, v171
	v_fma_f32 v171, v19, v19, v171
	v_fma_f32 v171, v20, v20, v171
	v_fma_f32 v171, v21, v21, v171
	v_cvt_pk_bf16_f32 v18, v18, v19
	v_cvt_pk_bf16_f32 v19, v20, v21
	global_store_dwordx2 v164, v[18:19], s[20:21] offset:1024
	v_lshlrev_b32_e32 v167, 16, v234
	v_and_b32_e32 v168, 0xffff0000, v234
	v_lshlrev_b32_e32 v169, 16, v235
	v_and_b32_e32 v170, 0xffff0000, v235
	v_add_f32_e32 v22, v22, v167
	v_add_f32_e32 v23, v23, v168
	v_add_f32_e32 v24, v24, v169
	v_add_f32_e32 v25, v25, v170
	v_fma_f32 v171, v22, v22, v171
	v_fma_f32 v171, v23, v23, v171
	v_fma_f32 v171, v24, v24, v171
	v_fma_f32 v171, v25, v25, v171
	v_cvt_pk_bf16_f32 v22, v22, v23
	v_cvt_pk_bf16_f32 v23, v24, v25
	global_store_dwordx2 v164, v[22:23], s[20:21] offset:1056
	v_lshlrev_b32_e32 v167, 16, v236
	v_and_b32_e32 v168, 0xffff0000, v236
	v_lshlrev_b32_e32 v169, 16, v237
	v_and_b32_e32 v170, 0xffff0000, v237
	v_add_f32_e32 v26, v26, v167
	v_add_f32_e32 v27, v27, v168
	v_add_f32_e32 v28, v28, v169
	v_add_f32_e32 v29, v29, v170
	v_fma_f32 v171, v26, v26, v171
	v_fma_f32 v171, v27, v27, v171
	v_fma_f32 v171, v28, v28, v171
	v_fma_f32 v171, v29, v29, v171
	v_cvt_pk_bf16_f32 v26, v26, v27
	v_cvt_pk_bf16_f32 v27, v28, v29
	global_store_dwordx2 v122, v[26:27], s[20:21] offset:1024
	v_lshlrev_b32_e32 v167, 16, v238
	v_and_b32_e32 v168, 0xffff0000, v238
	v_lshlrev_b32_e32 v169, 16, v239
	v_and_b32_e32 v170, 0xffff0000, v239
	v_add_f32_e32 v30, v30, v167
	v_add_f32_e32 v31, v31, v168
	v_add_f32_e32 v32, v32, v169
	v_add_f32_e32 v33, v33, v170
	v_fma_f32 v171, v30, v30, v171
	v_fma_f32 v171, v31, v31, v171
	v_fma_f32 v171, v32, v32, v171
	v_fma_f32 v171, v33, v33, v171
	v_cvt_pk_bf16_f32 v30, v30, v31
	v_cvt_pk_bf16_f32 v31, v32, v33
	global_store_dwordx2 v122, v[30:31], s[20:21] offset:1056
	v_mov_b32_e32 v167, v171
	s_nop 1
	v_permlane32_swap_b32_e32 v171, v167
	v_add_f32_e32 v171, v171, v167
	ds_swizzle_b32 v167, v171 offset:0x401f
	s_waitcnt lgkmcnt(0)
; DI u32x4 pack8(const float (&v)[8]) { u32x4 r = {pk2(v[0], v[1]), pk2(v[2], v[3]), pk2(v[4], v[5]), pk2(v[6], v[7])}; return r; }
; DI void tile_outproj(const Params& p, int l, const Chunk& ck, int tile, int next, PF& pf, char* smem) {
;     ...
;   const int row = tid >> 1, half = tid & 1; float ssq = 0.f;
;   u16* xb = (u16*)(p.ws + OFF_XB) + (size_t)(m0 + row) * 1024 + n0 + half * 64;
; #pragma unroll
;   for (int c8 = 0; c8 < 8; ++c8) {
;     float v[8], x[8]; cs_ld8(Cs, row, half * 64 + c8 * 8, v); unpack8(*(const u32x4*)(xb + c8 * 8), x);
; #pragma unroll
;     for (int j = 0; j < 8; ++j) { v[j] += x[j]; ssq += v[j] * v[j]; }
;     *(u32x4*)(xb + c8 * 8) = pack8(v);
;   }
;   ((float*)(p.ws + OFF_PSMID))[(size_t)(m0 + row) * 16 + ni * 2 + half] = ssq;
	v_add_f32_e32 v171, v171, v167
	v_cmp_gt_u32_e32 vcc, 16, v160
	s_and_saveexec_b64 s[98:99], vcc
	global_store_dword v166, v171, s[14:15] offset:1024
	s_or_b64 exec, exec, s[98:99]
	v_mov_b32_e32 v171, 0
	v_lshlrev_b32_e32 v167, 16, v240
	v_and_b32_e32 v168, 0xffff0000, v240
	v_lshlrev_b32_e32 v169, 16, v241
	v_and_b32_e32 v170, 0xffff0000, v241
	v_add_f32_e32 v34, v34, v167
	v_add_f32_e32 v35, v35, v168
	v_add_f32_e32 v36, v36, v169
	v_add_f32_e32 v37, v37, v170
	v_fma_f32 v171, v34, v34, v171
	v_fma_f32 v171, v35, v35, v171
	v_fma_f32 v171, v36, v36, v171
	v_fma_f32 v171, v37, v37, v171
	v_cvt_pk_bf16_f32 v34, v34, v35
	v_cvt_pk_bf16_f32 v35, v36, v37
	global_store_dwordx2 v164, v[34:35], s[20:21] offset:2048
	v_lshlrev_b32_e32 v167, 16, v242
	v_and_b32_e32 v168, 0xffff0000, v242
	v_lshlrev_b32_e32 v169, 16, v243
	v_and_b32_e32 v170, 0xffff0000, v243
	v_add_f32_e32 v38, v38, v167
	v_add_f32_e32 v39, v39, v168
	v_add_f32_e32 v40, v40, v169
	v_add_f32_e32 v41, v41, v170
	v_fma_f32 v171, v38, v38, v171
	v_fma_f32 v171, v39, v39, v171
	v_fma_f32 v171, v40, v40, v171
	v_fma_f32 v171, v41, v41, v171
	v_cvt_pk_bf16_f32 v38, v38, v39
	v_cvt_pk_bf16_f32 v39, v40, v41
	global_store_dwordx2 v164, v[38:39], s[20:21] offset:2080
	v_lshlrev_b32_e32 v167, 16, v244
	v_and_b32_e32 v168, 0xffff0000, v244
	v_lshlrev_b32_e32 v169, 16, v245
	v_and_b32_e32 v170, 0xffff0000, v245
	v_add_f32_e32 v42, v42, v167
	v_add_f32_e32 v43, v43, v168
	v_add_f32_e32 v44, v44, v169
	v_add_f32_e32 v45, v45, v170
	v_fma_f32 v171, v42, v42, v171
	v_fma_f32 v171, v43, v43, v171
	v_fma_f32 v171, v44, v44, v171
	v_fma_f32 v171, v45, v45, v171
	v_cvt_pk_bf16_f32 v42, v42, v43
	v_cvt_pk_bf16_f32 v43, v44, v45
	global_store_dwordx2 v122, v[42:43], s[20:21] offset:2048
	v_lshlrev_b32_e32 v167, 16, v246
	v_and_b32_e32 v168, 0xffff0000, v246
	v_lshlrev_b32_e32 v169, 16, v247
	v_and_b32_e32 v170, 0xffff0000, v247
	v_add_f32_e32 v46, v46, v167
	v_add_f32_e32 v47, v47, v168
	v_add_f32_e32 v48, v48, v169
	v_add_f32_e32 v49, v49, v170
	v_fma_f32 v171, v46, v46, v171
	v_fma_f32 v171, v47, v47, v171
	v_fma_f32 v171, v48, v48, v171
	v_fma_f32 v171, v49, v49, v171
	v_cvt_pk_bf16_f32 v46, v46, v47
	v_cvt_pk_bf16_f32 v47, v48, v49
	global_store_dwordx2 v122, v[46:47], s[20:21] offset:2080
	v_mov_b32_e32 v167, v171
	s_nop 1
	v_permlane32_swap_b32_e32 v171, v167
	v_add_f32_e32 v171, v171, v167
	ds_swizzle_b32 v167, v171 offset:0x401f
	s_waitcnt lgkmcnt(0)
	v_add_f32_e32 v171, v171, v167
	v_cmp_gt_u32_e32 vcc, 16, v160
	s_and_saveexec_b64 s[98:99], vcc
	global_store_dword v166, v171, s[14:15] offset:2048
	s_or_b64 exec, exec, s[98:99]
	v_mov_b32_e32 v171, 0
	v_lshlrev_b32_e32 v167, 16, v248
	v_and_b32_e32 v168, 0xffff0000, v248
	v_lshlrev_b32_e32 v169, 16, v249
	v_and_b32_e32 v170, 0xffff0000, v249
	v_add_f32_e32 v50, v50, v167
	v_add_f32_e32 v51, v51, v168
	v_add_f32_e32 v52, v52, v169
	v_add_f32_e32 v53, v53, v170
	v_fma_f32 v171, v50, v50, v171
	v_fma_f32 v171, v51, v51, v171
	v_fma_f32 v171, v52, v52, v171
	v_fma_f32 v171, v53, v53, v171
	v_cvt_pk_bf16_f32 v50, v50, v51
	v_cvt_pk_bf16_f32 v51, v52, v53
	global_store_dwordx2 v164, v[50:51], s[20:21] offset:3072
	v_lshlrev_b32_e32 v167, 16, v250
	v_and_b32_e32 v168, 0xffff0000, v250
	v_lshlrev_b32_e32 v169, 16, v251
	v_and_b32_e32 v170, 0xffff0000, v251
	v_add_f32_e32 v54, v54, v167
	v_add_f32_e32 v55, v55, v168
	v_add_f32_e32 v56, v56, v169
	v_add_f32_e32 v57, v57, v170
	v_fma_f32 v171, v54, v54, v171
	v_fma_f32 v171, v55, v55, v171
	v_fma_f32 v171, v56, v56, v171
	v_fma_f32 v171, v57, v57, v171
	v_cvt_pk_bf16_f32 v54, v54, v55
	v_cvt_pk_bf16_f32 v55, v56, v57
	global_store_dwordx2 v164, v[54:55], s[20:21] offset:3104
	v_lshlrev_b32_e32 v167, 16, v156
	v_and_b32_e32 v168, 0xffff0000, v156
	v_lshlrev_b32_e32 v169, 16, v157
	v_and_b32_e32 v170, 0xffff0000, v157
	v_add_f32_e32 v58, v58, v167
	v_add_f32_e32 v59, v59, v168
	v_add_f32_e32 v60, v60, v169
	v_add_f32_e32 v61, v61, v170
	v_fma_f32 v171, v58, v58, v171
	v_fma_f32 v171, v59, v59, v171
	v_fma_f32 v171, v60, v60, v171
	v_fma_f32 v171, v61, v61, v171
	v_cvt_pk_bf16_f32 v58, v58, v59
	v_cvt_pk_bf16_f32 v59, v60, v61
	global_store_dwordx2 v122, v[58:59], s[20:21] offset:3072
	v_lshlrev_b32_e32 v167, 16, v158
	v_and_b32_e32 v168, 0xffff0000, v158
	v_lshlrev_b32_e32 v169, 16, v159
	v_and_b32_e32 v170, 0xffff0000, v159
	v_add_f32_e32 v62, v62, v167
	v_add_f32_e32 v63, v63, v168
	v_add_f32_e32 v64, v64, v169
	v_add_f32_e32 v65, v65, v170
	v_fma_f32 v171, v62, v62, v171
	v_fma_f32 v171, v63, v63, v171
	v_fma_f32 v171, v64, v64, v171
	v_fma_f32 v171, v65, v65, v171
	v_cvt_pk_bf16_f32 v62, v62, v63
	v_cvt_pk_bf16_f32 v63, v64, v65
	global_store_dwordx2 v122, v[62:63], s[20:21] offset:3104
	v_mov_b32_e32 v167, v171
	s_nop 1
	v_permlane32_swap_b32_e32 v171, v167
	v_add_f32_e32 v171, v171, v167
	ds_swizzle_b32 v167, v171 offset:0x401f
	s_waitcnt lgkmcnt(0)
	v_add_f32_e32 v171, v171, v167
	v_cmp_gt_u32_e32 vcc, 16, v160
	s_and_saveexec_b64 s[98:99], vcc
	global_store_dword v166, v171, s[14:15] offset:3072
	s_or_b64 exec, exec, s[98:99]
	v_add_u32_e32 v164, 0x400000, v164
	v_add_u32_e32 v122, 0x400000, v122
	global_load_dwordx2 v[224:225], v164, s[20:21] offset:0
	global_load_dwordx2 v[226:227], v164, s[20:21] offset:32
	global_load_dwordx2 v[228:229], v122, s[20:21] offset:0
	global_load_dwordx2 v[230:231], v122, s[20:21] offset:32
	global_load_dwordx2 v[232:233], v164, s[20:21] offset:1024
	global_load_dwordx2 v[234:235], v164, s[20:21] offset:1056
	global_load_dwordx2 v[236:237], v122, s[20:21] offset:1024
	global_load_dwordx2 v[238:239], v122, s[20:21] offset:1056
	global_load_dwordx2 v[240:241], v164, s[20:21] offset:2048
	global_load_dwordx2 v[242:243], v164, s[20:21] offset:2080
	global_load_dwordx2 v[244:245], v122, s[20:21] offset:2048
	global_load_dwordx2 v[246:247], v122, s[20:21] offset:2080
	global_load_dwordx2 v[248:249], v164, s[20:21] offset:3072
	global_load_dwordx2 v[250:251], v164, s[20:21] offset:3104
	global_load_dwordx2 v[156:157], v122, s[20:21] offset:3072
	global_load_dwordx2 v[158:159], v122, s[20:21] offset:3104
	s_waitcnt vmcnt(0)
; DI u32x4 pack8(const float (&v)[8]) { u32x4 r = {pk2(v[0], v[1]), pk2(v[2], v[3]), pk2(v[4], v[5]), pk2(v[6], v[7])}; return r; }
; DI void tile_outproj(const Params& p, int l, const Chunk& ck, int tile, int next, PF& pf, char* smem) {
;     ...
;   const int row = tid >> 1, half = tid & 1; float ssq = 0.f;
;   u16* xb = (u16*)(p.ws + OFF_XB) + (size_t)(m0 + row) * 1024 + n0 + half * 64;
; #pragma unroll
;   for (int c8 = 0; c8 < 8; ++c8) {
;     float v[8], x[8]; cs_ld8(Cs, row, half * 64 + c8 * 8, v); unpack8(*(const u32x4*)(xb + c8 * 8), x);
; #pragma unroll
;     for (int j = 0; j < 8; ++j) { v[j] += x[j]; ssq += v[j] * v[j]; }
;     *(u32x4*)(xb + c8 * 8) = pack8(v);
;   }
;   ((float*)(p.ws + OFF_PSMID))[(size_t)(m0 + row) * 16 + ni * 2 + half] = ssq;
	v_mov_b32_e32 v171, 0
	v_lshlrev_b32_e32 v167, 16, v224
	v_and_b32_e32 v168, 0xffff0000, v224
	v_lshlrev_b32_e32 v169, 16, v225
	v_and_b32_e32 v170, 0xffff0000, v225
	v_add_f32_e32 v74, v74, v167
	v_add_f32_e32 v75, v75, v168
	v_add_f32_e32 v76, v76, v169
	v_add_f32_e32 v77, v77, v170
	v_fma_f32 v171, v74, v74, v171
	v_fma_f32 v171, v75, v75, v171
	v_fma_f32 v171, v76, v76, v171
	v_fma_f32 v171, v77, v77, v171
	v_cvt_pk_bf16_f32 v74, v74, v75
	v_cvt_pk_bf16_f32 v75, v76, v77
	global_store_dwordx2 v164, v[74:75], s[20:21]
	v_lshlrev_b32_e32 v167, 16, v226
	v_and_b32_e32 v168, 0xffff0000, v226
	v_lshlrev_b32_e32 v169, 16, v227
	v_and_b32_e32 v170, 0xffff0000, v227
	v_add_f32_e32 v78, v78, v167
	v_add_f32_e32 v79, v79, v168
	v_add_f32_e32 v80, v80, v169
	v_add_f32_e32 v81, v81, v170
	v_fma_f32 v171, v78, v78, v171
	v_fma_f32 v171, v79, v79, v171
	v_fma_f32 v171, v80, v80, v171
	v_fma_f32 v171, v81, v81, v171
	v_cvt_pk_bf16_f32 v78, v78, v79
	v_cvt_pk_bf16_f32 v79, v80, v81
	global_store_dwordx2 v164, v[78:79], s[20:21] offset:32
	v_lshlrev_b32_e32 v167, 16, v228
	v_and_b32_e32 v168, 0xffff0000, v228
	v_lshlrev_b32_e32 v169, 16, v229
	v_and_b32_e32 v170, 0xffff0000, v229
	v_add_f32_e32 v82, v82, v167
	v_add_f32_e32 v83, v83, v168
	v_add_f32_e32 v84, v84, v169
	v_add_f32_e32 v85, v85, v170
	v_fma_f32 v171, v82, v82, v171
	v_fma_f32 v171, v83, v83, v171
	v_fma_f32 v171, v84, v84, v171
	v_fma_f32 v171, v85, v85, v171
	v_cvt_pk_bf16_f32 v82, v82, v83
	v_cvt_pk_bf16_f32 v83, v84, v85
	global_store_dwordx2 v122, v[82:83], s[20:21]
	v_lshlrev_b32_e32 v167, 16, v230
	v_and_b32_e32 v168, 0xffff0000, v230
	v_lshlrev_b32_e32 v169, 16, v231
	v_and_b32_e32 v170, 0xffff0000, v231
	v_add_f32_e32 v86, v86, v167
	v_add_f32_e32 v87, v87, v168
	v_add_f32_e32 v88, v88, v169
	v_add_f32_e32 v89, v89, v170
	v_fma_f32 v171, v86, v86, v171
	v_fma_f32 v171, v87, v87, v171
	v_fma_f32 v171, v88, v88, v171
	v_fma_f32 v171, v89, v89, v171
	v_cvt_pk_bf16_f32 v86, v86, v87
	v_cvt_pk_bf16_f32 v87, v88, v89
	global_store_dwordx2 v122, v[86:87], s[20:21] offset:32
	v_mov_b32_e32 v167, v171
	s_nop 1
	v_permlane32_swap_b32_e32 v171, v167
	v_add_f32_e32 v171, v171, v167
	ds_swizzle_b32 v167, v171 offset:0x401f
	s_waitcnt lgkmcnt(0)
	v_add_f32_e32 v171, v171, v167
	v_cmp_gt_u32_e32 vcc, 16, v160
	s_and_saveexec_b64 s[98:99], vcc
	global_store_dword v166, v171, s[14:15] offset:8
	s_or_b64 exec, exec, s[98:99]
	v_mov_b32_e32 v171, 0
	v_lshlrev_b32_e32 v167, 16, v232
	v_and_b32_e32 v168, 0xffff0000, v232
	v_lshlrev_b32_e32 v169, 16, v233
	v_and_b32_e32 v170, 0xffff0000, v233
	v_add_f32_e32 v90, v90, v167
	v_add_f32_e32 v91, v91, v168
	v_add_f32_e32 v92, v92, v169
	v_add_f32_e32 v93, v93, v170
	v_fma_f32 v171, v90, v90, v171
	v_fma_f32 v171, v91, v91, v171
	v_fma_f32 v171, v92, v92, v171
	v_fma_f32 v171, v93, v93, v171
	v_cvt_pk_bf16_f32 v90, v90, v91
	v_cvt_pk_bf16_f32 v91, v92, v93
	global_store_dwordx2 v164, v[90:91], s[20:21] offset:1024
	v_lshlrev_b32_e32 v167, 16, v234
	v_and_b32_e32 v168, 0xffff0000, v234
	v_lshlrev_b32_e32 v169, 16, v235
	v_and_b32_e32 v170, 0xffff0000, v235
	v_add_f32_e32 v94, v94, v167
	v_add_f32_e32 v95, v95, v168
	v_add_f32_e32 v96, v96, v169
	v_add_f32_e32 v97, v97, v170
	v_fma_f32 v171, v94, v94, v171
	v_fma_f32 v171, v95, v95, v171
	v_fma_f32 v171, v96, v96, v171
	v_fma_f32 v171, v97, v97, v171
	v_cvt_pk_bf16_f32 v94, v94, v95
	v_cvt_pk_bf16_f32 v95, v96, v97
	global_store_dwordx2 v164, v[94:95], s[20:21] offset:1056
	v_lshlrev_b32_e32 v167, 16, v236
	v_and_b32_e32 v168, 0xffff0000, v236
	v_lshlrev_b32_e32 v169, 16, v237
	v_and_b32_e32 v170, 0xffff0000, v237
	v_add_f32_e32 v98, v98, v167
	v_add_f32_e32 v99, v99, v168
	v_add_f32_e32 v100, v100, v169
	v_add_f32_e32 v101, v101, v170
	v_fma_f32 v171, v98, v98, v171
	v_fma_f32 v171, v99, v99, v171
	v_fma_f32 v171, v100, v100, v171
	v_fma_f32 v171, v101, v101, v171
	v_cvt_pk_bf16_f32 v98, v98, v99
	v_cvt_pk_bf16_f32 v99, v100, v101
	global_store_dwordx2 v122, v[98:99], s[20:21] offset:1024
	v_lshlrev_b32_e32 v167, 16, v238
	v_and_b32_e32 v168, 0xffff0000, v238
	v_lshlrev_b32_e32 v169, 16, v239
	v_and_b32_e32 v170, 0xffff0000, v239
	v_add_f32_e32 v102, v102, v167
	v_add_f32_e32 v103, v103, v168
	v_add_f32_e32 v104, v104, v169
	v_add_f32_e32 v105, v105, v170
	v_fma_f32 v171, v102, v102, v171
	v_fma_f32 v171, v103, v103, v171
	v_fma_f32 v171, v104, v104, v171
	v_fma_f32 v171, v105, v105, v171
	v_cvt_pk_bf16_f32 v102, v102, v103
	v_cvt_pk_bf16_f32 v103, v104, v105
	global_store_dwordx2 v122, v[102:103], s[20:21] offset:1056
	v_mov_b32_e32 v167, v171
	s_nop 1
	v_permlane32_swap_b32_e32 v171, v167
	v_add_f32_e32 v171, v171, v167
	ds_swizzle_b32 v167, v171 offset:0x401f
	s_waitcnt lgkmcnt(0)
; DI u32x4 pack8(const float (&v)[8]) { u32x4 r = {pk2(v[0], v[1]), pk2(v[2], v[3]), pk2(v[4], v[5]), pk2(v[6], v[7])}; return r; }
; DI void tile_outproj(const Params& p, int l, const Chunk& ck, int tile, int next, PF& pf, char* smem) {
;     ...
;   const int row = tid >> 1, half = tid & 1; float ssq = 0.f;
;   u16* xb = (u16*)(p.ws + OFF_XB) + (size_t)(m0 + row) * 1024 + n0 + half * 64;
; #pragma unroll
;   for (int c8 = 0; c8 < 8; ++c8) {
;     float v[8], x[8]; cs_ld8(Cs, row, half * 64 + c8 * 8, v); unpack8(*(const u32x4*)(xb + c8 * 8), x);
; #pragma unroll
;     for (int j = 0; j < 8; ++j) { v[j] += x[j]; ssq += v[j] * v[j]; }
;     *(u32x4*)(xb + c8 * 8) = pack8(v);
;   }
;   ((float*)(p.ws + OFF_PSMID))[(size_t)(m0 + row) * 16 + ni * 2 + half] = ssq;
	v_add_f32_e32 v171, v171, v167
	v_cmp_gt_u32_e32 vcc, 16, v160
	s_and_saveexec_b64 s[98:99], vcc
	global_store_dword v166, v171, s[14:15] offset:1032
	s_or_b64 exec, exec, s[98:99]
	v_mov_b32_e32 v171, 0
	v_lshlrev_b32_e32 v167, 16, v240
	v_and_b32_e32 v168, 0xffff0000, v240
	v_lshlrev_b32_e32 v169, 16, v241
	v_and_b32_e32 v170, 0xffff0000, v241
	v_add_f32_e32 v106, v106, v167
	v_add_f32_e32 v107, v107, v168
	v_add_f32_e32 v108, v108, v169
	v_add_f32_e32 v109, v109, v170
	v_fma_f32 v171, v106, v106, v171
	v_fma_f32 v171, v107, v107, v171
	v_fma_f32 v171, v108, v108, v171
	v_fma_f32 v171, v109, v109, v171
	v_cvt_pk_bf16_f32 v106, v106, v107
	v_cvt_pk_bf16_f32 v107, v108, v109
	global_store_dwordx2 v164, v[106:107], s[20:21] offset:2048
	v_lshlrev_b32_e32 v167, 16, v242
	v_and_b32_e32 v168, 0xffff0000, v242
	v_lshlrev_b32_e32 v169, 16, v243
	v_and_b32_e32 v170, 0xffff0000, v243
	v_add_f32_e32 v110, v110, v167
	v_add_f32_e32 v111, v111, v168
	v_add_f32_e32 v112, v112, v169
	v_add_f32_e32 v113, v113, v170
	v_fma_f32 v171, v110, v110, v171
	v_fma_f32 v171, v111, v111, v171
	v_fma_f32 v171, v112, v112, v171
	v_fma_f32 v171, v113, v113, v171
	v_cvt_pk_bf16_f32 v110, v110, v111
	v_cvt_pk_bf16_f32 v111, v112, v113
	global_store_dwordx2 v164, v[110:111], s[20:21] offset:2080
	v_lshlrev_b32_e32 v167, 16, v244
	v_and_b32_e32 v168, 0xffff0000, v244
	v_lshlrev_b32_e32 v169, 16, v245
	v_and_b32_e32 v170, 0xffff0000, v245
	v_add_f32_e32 v114, v114, v167
	v_add_f32_e32 v115, v115, v168
	v_add_f32_e32 v116, v116, v169
	v_add_f32_e32 v117, v117, v170
	v_fma_f32 v171, v114, v114, v171
	v_fma_f32 v171, v115, v115, v171
	v_fma_f32 v171, v116, v116, v171
	v_fma_f32 v171, v117, v117, v171
	v_cvt_pk_bf16_f32 v114, v114, v115
	v_cvt_pk_bf16_f32 v115, v116, v117
	global_store_dwordx2 v122, v[114:115], s[20:21] offset:2048
	v_lshlrev_b32_e32 v167, 16, v246
	v_and_b32_e32 v168, 0xffff0000, v246
	v_lshlrev_b32_e32 v169, 16, v247
	v_and_b32_e32 v170, 0xffff0000, v247
	v_add_f32_e32 v118, v118, v167
	v_add_f32_e32 v119, v119, v168
	v_add_f32_e32 v120, v120, v169
	v_add_f32_e32 v121, v121, v170
	v_fma_f32 v171, v118, v118, v171
	v_fma_f32 v171, v119, v119, v171
	v_fma_f32 v171, v120, v120, v171
	v_fma_f32 v171, v121, v121, v171
	v_cvt_pk_bf16_f32 v118, v118, v119
	v_cvt_pk_bf16_f32 v119, v120, v121
	global_store_dwordx2 v122, v[118:119], s[20:21] offset:2080
	v_mov_b32_e32 v167, v171
	s_nop 1
	v_permlane32_swap_b32_e32 v171, v167
	v_add_f32_e32 v171, v171, v167
	ds_swizzle_b32 v167, v171 offset:0x401f
	s_waitcnt lgkmcnt(0)
	v_add_f32_e32 v171, v171, v167
	v_cmp_gt_u32_e32 vcc, 16, v160
	s_and_saveexec_b64 s[98:99], vcc
	global_store_dword v166, v171, s[14:15] offset:2056
	s_or_b64 exec, exec, s[98:99]
	v_mov_b32_e32 v171, 0
	v_lshlrev_b32_e32 v167, 16, v248
	v_and_b32_e32 v168, 0xffff0000, v248
	v_lshlrev_b32_e32 v169, 16, v249
	v_and_b32_e32 v170, 0xffff0000, v249
	v_add_f32_e32 v208, v208, v167
	v_add_f32_e32 v209, v209, v168
	v_add_f32_e32 v210, v210, v169
	v_add_f32_e32 v211, v211, v170
	v_fma_f32 v171, v208, v208, v171
	v_fma_f32 v171, v209, v209, v171
	v_fma_f32 v171, v210, v210, v171
	v_fma_f32 v171, v211, v211, v171
	v_cvt_pk_bf16_f32 v208, v208, v209
	v_cvt_pk_bf16_f32 v209, v210, v211
	global_store_dwordx2 v164, v[208:209], s[20:21] offset:3072
	v_lshlrev_b32_e32 v167, 16, v250
	v_and_b32_e32 v168, 0xffff0000, v250
	v_lshlrev_b32_e32 v169, 16, v251
	v_and_b32_e32 v170, 0xffff0000, v251
	v_add_f32_e32 v212, v212, v167
	v_add_f32_e32 v213, v213, v168
	v_add_f32_e32 v214, v214, v169
	v_add_f32_e32 v215, v215, v170
	v_fma_f32 v171, v212, v212, v171
	v_fma_f32 v171, v213, v213, v171
	v_fma_f32 v171, v214, v214, v171
	v_fma_f32 v171, v215, v215, v171
	v_cvt_pk_bf16_f32 v212, v212, v213
	v_cvt_pk_bf16_f32 v213, v214, v215
	global_store_dwordx2 v164, v[212:213], s[20:21] offset:3104
	v_lshlrev_b32_e32 v167, 16, v156
	v_and_b32_e32 v168, 0xffff0000, v156
	v_lshlrev_b32_e32 v169, 16, v157
	v_and_b32_e32 v170, 0xffff0000, v157
	v_add_f32_e32 v216, v216, v167
	v_add_f32_e32 v217, v217, v168
	v_add_f32_e32 v218, v218, v169
	v_add_f32_e32 v219, v219, v170
	v_fma_f32 v171, v216, v216, v171
	v_fma_f32 v171, v217, v217, v171
	v_fma_f32 v171, v218, v218, v171
	v_fma_f32 v171, v219, v219, v171
	v_cvt_pk_bf16_f32 v216, v216, v217
	v_cvt_pk_bf16_f32 v217, v218, v219
	global_store_dwordx2 v122, v[216:217], s[20:21] offset:3072
	v_lshlrev_b32_e32 v167, 16, v158
	v_and_b32_e32 v168, 0xffff0000, v158
	v_lshlrev_b32_e32 v169, 16, v159
	v_and_b32_e32 v170, 0xffff0000, v159
	v_add_f32_e32 v220, v220, v167
	v_add_f32_e32 v221, v221, v168
	v_add_f32_e32 v222, v222, v169
	v_add_f32_e32 v223, v223, v170
	v_fma_f32 v171, v220, v220, v171
	v_fma_f32 v171, v221, v221, v171
	v_fma_f32 v171, v222, v222, v171
	v_fma_f32 v171, v223, v223, v171
	v_cvt_pk_bf16_f32 v220, v220, v221
	v_cvt_pk_bf16_f32 v221, v222, v223
	global_store_dwordx2 v122, v[220:221], s[20:21] offset:3104
	v_mov_b32_e32 v167, v171
	s_nop 1
	v_permlane32_swap_b32_e32 v171, v167
	v_add_f32_e32 v171, v171, v167
	ds_swizzle_b32 v167, v171 offset:0x401f
	s_waitcnt lgkmcnt(0)
	v_add_f32_e32 v171, v171, v167
	v_cmp_gt_u32_e32 vcc, 16, v160
	s_and_saveexec_b64 s[98:99], vcc
	global_store_dword v166, v171, s[14:15] offset:3080
	s_or_b64 exec, exec, s[98:99]
	s_branch .LBB1_254

; #define BLOAD(A_, B_, kt) do { _Pragma("unroll") for (int i = 0; i < 4; ++i) { \
;     A_[i] = *(const u32x4*)((const char*)Ap + (aoff + (unsigned)(32 * i * lda + (kt) * 64) * 2u)); B_[i] = *(const u32x4*)((const char*)Wt + (woff + (unsigned)(32 * i * K + (kt) * 64) * 2u)); } } while (0)
; #define BLOAD(A_, B_, kt) do { _Pragma("unroll") for (int i = 0; i < 4; ++i) { \
;     A_[i] = *(const u32x4*)((const char*)Ap + (aoff + (unsigned)(32 * i * lda + (kt) * 64) * 2u)); B_[i] = *(const u32x4*)((const char*)Wt + (woff + (unsigned)(32 * i * K + (kt) * 64) * 2u)); } } while (0)
; #define BSTORE(A_, B_, buf) do { _Pragma("unroll") for (int i = 0; i < 4; ++i) { \
;     *(u32x4*)&As[(buf) * GBUF + (srow + 32 * i) * LDT + sc8] = A_[i]; \
;     *(u32x4*)&Bs[(buf) * GBUF + (srow + 32 * i) * LDT + sc8] = B_[i]; } } while (0)
; template <int NK>
; DI void gemm_run(PF& pf, const u16* __restrict__ Ap, int lda, const u16* __restrict__ Wt, f32x16 (&acc)[2][2], char* smem) {
;     ...
;   __builtin_amdgcn_s_setprio(0);
;   __syncthreads();
;   BSTORE(pf.a0, pf.b0, 0);
;   BLOAD(pf.a0, pf.b0, 2);
;   __syncthreads();
; #pragma unroll
;   for (int kt = 0; kt < nk; kt += 2) {
;     BCOMP(0);
;     BSTORE(pf.a1, pf.b1, 1);
;     if (kt + 3 < nk) BLOAD(pf.a1, pf.b1, kt + 3);
;     __syncthreads();
;     BCOMP(1);
;     if (kt + 2 < nk) { BSTORE(pf.a0, pf.b0, 0); if (kt + 4 < nk) BLOAD(pf.a0, pf.b0, kt + 4); }
;     __syncthreads();
;   }
.Linp_kloop:
	s_waitcnt vmcnt(6)
	s_barrier
	ds_read_b128 v[224:227], v126 offset:0
	ds_read_b128 v[240:243], v128 offset:0
	ds_read_b128 v[244:247], v128 offset:1024
	ds_read_b128 v[248:251], v128 offset:2048
	ds_read_b128 v[156:159], v128 offset:3072
	ds_read_b128 v[228:231], v126 offset:1024
	s_waitcnt lgkmcnt(4)
	v_mfma_f32_16x16x32_bf16 v[2:5], v[224:227], v[240:243], v[2:5]
	ds_read_b128 v[232:235], v126 offset:2048
	s_waitcnt lgkmcnt(4)
	v_mfma_f32_16x16x32_bf16 v[6:9], v[224:227], v[244:247], v[6:9]
	ds_read_b128 v[236:239], v126 offset:3072
	s_waitcnt lgkmcnt(4)
	v_mfma_f32_16x16x32_bf16 v[10:13], v[224:227], v[248:251], v[10:13]
	s_add_u32 m0, s46, 0xc000
	s_add_u32 s48, s48, 0x100000
	s_addc_u32 s49, s49, 0
	global_load_lds_dwordx4 v138, s[48:49]
	global_load_lds_dwordx4 v139, s[48:49] offset:1024
	s_add_u32 m0, s47, 0xc000
	s_add_u32 s50, s50, s13
	s_addc_u32 s51, s51, 0
	global_load_lds_dwordx4 v140, s[50:51]
	global_load_lds_dwordx4 v141, s[50:51] offset:1024
	global_load_lds_dwordx4 v142, s[50:51] offset:2048
	global_load_lds_dwordx4 v143, s[50:51] offset:3072
	s_waitcnt lgkmcnt(3)
	v_mfma_f32_16x16x32_bf16 v[14:17], v[224:227], v[156:159], v[14:17]
	s_waitcnt lgkmcnt(2)
	v_mfma_f32_16x16x32_bf16 v[18:21], v[228:231], v[240:243], v[18:21]
	ds_read_b128 v[160:163], v128 offset:8192
	v_mfma_f32_16x16x32_bf16 v[22:25], v[228:231], v[244:247], v[22:25]
	ds_read_b128 v[164:167], v128 offset:9216
	v_mfma_f32_16x16x32_bf16 v[26:29], v[228:231], v[248:251], v[26:29]
	ds_read_b128 v[168:171], v128 offset:10240
	v_mfma_f32_16x16x32_bf16 v[30:33], v[228:231], v[156:159], v[30:33]
	ds_read_b128 v[122:125], v128 offset:11264
	s_waitcnt lgkmcnt(5)
	v_mfma_f32_16x16x32_bf16 v[34:37], v[232:235], v[240:243], v[34:37]
	v_mfma_f32_16x16x32_bf16 v[38:41], v[232:235], v[244:247], v[38:41]
	v_mfma_f32_16x16x32_bf16 v[42:45], v[232:235], v[248:251], v[42:45]
	v_mfma_f32_16x16x32_bf16 v[46:49], v[232:235], v[156:159], v[46:49]
	s_waitcnt lgkmcnt(4)
	v_mfma_f32_16x16x32_bf16 v[50:53], v[236:239], v[240:243], v[50:53]
	v_mfma_f32_16x16x32_bf16 v[54:57], v[236:239], v[244:247], v[54:57]
	v_mfma_f32_16x16x32_bf16 v[58:61], v[236:239], v[248:251], v[58:61]
	v_mfma_f32_16x16x32_bf16 v[62:65], v[236:239], v[156:159], v[62:65]
	s_waitcnt lgkmcnt(3)
	v_mfma_f32_16x16x32_bf16 v[74:77], v[224:227], v[160:163], v[74:77]
	s_waitcnt lgkmcnt(2)
	v_mfma_f32_16x16x32_bf16 v[78:81], v[224:227], v[164:167], v[78:81]
	s_waitcnt lgkmcnt(1)
	v_mfma_f32_16x16x32_bf16 v[82:85], v[224:227], v[168:171], v[82:85]
	s_waitcnt lgkmcnt(0)
	v_mfma_f32_16x16x32_bf16 v[86:89], v[224:227], v[122:125], v[86:89]
	v_mfma_f32_16x16x32_bf16 v[90:93], v[228:231], v[160:163], v[90:93]
	v_mfma_f32_16x16x32_bf16 v[94:97], v[228:231], v[164:167], v[94:97]
	v_mfma_f32_16x16x32_bf16 v[98:101], v[228:231], v[168:171], v[98:101]
	v_mfma_f32_16x16x32_bf16 v[102:105], v[228:231], v[122:125], v[102:105]
	v_mfma_f32_16x16x32_bf16 v[106:109], v[232:235], v[160:163], v[106:109]
	v_mfma_f32_16x16x32_bf16 v[110:113], v[232:235], v[164:167], v[110:113]
	v_mfma_f32_16x16x32_bf16 v[114:117], v[232:235], v[168:171], v[114:117]
	v_mfma_f32_16x16x32_bf16 v[118:121], v[232:235], v[122:125], v[118:121]
	v_mfma_f32_16x16x32_bf16 v[208:211], v[236:239], v[160:163], v[208:211]
	v_mfma_f32_16x16x32_bf16 v[212:215], v[236:239], v[164:167], v[212:215]
	v_mfma_f32_16x16x32_bf16 v[216:219], v[236:239], v[168:171], v[216:219]
	v_mfma_f32_16x16x32_bf16 v[220:223], v[236:239], v[122:125], v[220:223]
	s_waitcnt vmcnt(6)
	s_barrier
	ds_read_b128 v[224:227], v126 offset:24576
	ds_read_b128 v[240:243], v128 offset:24576
	ds_read_b128 v[244:247], v128 offset:25600
	ds_read_b128 v[248:251], v128 offset:26624
	ds_read_b128 v[156:159], v128 offset:27648
	ds_read_b128 v[228:231], v126 offset:25600
	s_waitcnt lgkmcnt(4)
	v_mfma_f32_16x16x32_bf16 v[2:5], v[224:227], v[240:243], v[2:5]
	ds_read_b128 v[232:235], v126 offset:26624
	s_waitcnt lgkmcnt(4)
	v_mfma_f32_16x16x32_bf16 v[6:9], v[224:227], v[244:247], v[6:9]
	ds_read_b128 v[236:239], v126 offset:27648
	s_waitcnt lgkmcnt(4)
	v_mfma_f32_16x16x32_bf16 v[10:13], v[224:227], v[248:251], v[10:13]
	s_add_u32 m0, s46, 0x0
	s_add_u32 s48, s48, 0x100000
	s_addc_u32 s49, s49, 0
	global_load_lds_dwordx4 v138, s[48:49]
	global_load_lds_dwordx4 v139, s[48:49] offset:1024
	s_add_u32 m0, s47, 0x0
	s_add_u32 s50, s50, s13
	s_addc_u32 s51, s51, 0
	global_load_lds_dwordx4 v140, s[50:51]
	global_load_lds_dwordx4 v141, s[50:51] offset:1024
	global_load_lds_dwordx4 v142, s[50:51] offset:2048
	global_load_lds_dwordx4 v143, s[50:51] offset:3072
	s_waitcnt lgkmcnt(3)
	v_mfma_f32_16x16x32_bf16 v[14:17], v[224:227], v[156:159], v[14:17]
	s_waitcnt lgkmcnt(2)
	v_mfma_f32_16x16x32_bf16 v[18:21], v[228:231], v[240:243], v[18:21]
	ds_read_b128 v[160:163], v128 offset:32768
	v_mfma_f32_16x16x32_bf16 v[22:25], v[228:231], v[244:247], v[22:25]
	ds_read_b128 v[164:167], v128 offset:33792
	v_mfma_f32_16x16x32_bf16 v[26:29], v[228:231], v[248:251], v[26:29]
	ds_read_b128 v[168:171], v128 offset:34816
	v_mfma_f32_16x16x32_bf16 v[30:33], v[228:231], v[156:159], v[30:33]
	ds_read_b128 v[122:125], v128 offset:35840
	s_waitcnt lgkmcnt(5)
	v_mfma_f32_16x16x32_bf16 v[34:37], v[232:235], v[240:243], v[34:37]
	v_mfma_f32_16x16x32_bf16 v[38:41], v[232:235], v[244:247], v[38:41]
	v_mfma_f32_16x16x32_bf16 v[42:45], v[232:235], v[248:251], v[42:45]
	v_mfma_f32_16x16x32_bf16 v[46:49], v[232:235], v[156:159], v[46:49]
	s_waitcnt lgkmcnt(4)
	v_mfma_f32_16x16x32_bf16 v[50:53], v[236:239], v[240:243], v[50:53]
	v_mfma_f32_16x16x32_bf16 v[54:57], v[236:239], v[244:247], v[54:57]
	v_mfma_f32_16x16x32_bf16 v[58:61], v[236:239], v[248:251], v[58:61]
	v_mfma_f32_16x16x32_bf16 v[62:65], v[236:239], v[156:159], v[62:65]
	s_waitcnt lgkmcnt(3)
	v_mfma_f32_16x16x32_bf16 v[74:77], v[224:227], v[160:163], v[74:77]
	s_waitcnt lgkmcnt(2)
	v_mfma_f32_16x16x32_bf16 v[78:81], v[224:227], v[164:167], v[78:81]
	s_waitcnt lgkmcnt(1)
	v_mfma_f32_16x16x32_bf16 v[82:85], v[224:227], v[168:171], v[82:85]
	s_waitcnt lgkmcnt(0)
	v_mfma_f32_16x16x32_bf16 v[86:89], v[224:227], v[122:125], v[86:89]
	v_mfma_f32_16x16x32_bf16 v[90:93], v[228:231], v[160:163], v[90:93]
	v_mfma_f32_16x16x32_bf16 v[94:97], v[228:231], v[164:167], v[94:97]
	v_mfma_f32_16x16x32_bf16 v[98:101], v[228:231], v[168:171], v[98:101]
	v_mfma_f32_16x16x32_bf16 v[102:105], v[228:231], v[122:125], v[102:105]
	v_mfma_f32_16x16x32_bf16 v[106:109], v[232:235], v[160:163], v[106:109]
	v_mfma_f32_16x16x32_bf16 v[110:113], v[232:235], v[164:167], v[110:113]
	v_mfma_f32_16x16x32_bf16 v[114:117], v[232:235], v[168:171], v[114:117]
	v_mfma_f32_16x16x32_bf16 v[118:121], v[232:235], v[122:125], v[118:121]
	v_mfma_f32_16x16x32_bf16 v[208:211], v[236:239], v[160:163], v[208:211]
	v_mfma_f32_16x16x32_bf16 v[212:215], v[236:239], v[164:167], v[212:215]
	v_mfma_f32_16x16x32_bf16 v[216:219], v[236:239], v[168:171], v[216:219]
	v_mfma_f32_16x16x32_bf16 v[220:223], v[236:239], v[122:125], v[220:223]
	s_waitcnt vmcnt(6)
	s_barrier
; #define BLOAD(A_, B_, kt) do { _Pragma("unroll") for (int i = 0; i < 4; ++i) { \
;     A_[i] = *(const u32x4*)((const char*)Ap + (aoff + (unsigned)(32 * i * lda + (kt) * 64) * 2u)); B_[i] = *(const u32x4*)((const char*)Wt + (woff + (unsigned)(32 * i * K + (kt) * 64) * 2u)); } } while (0)
; #define BLOAD(A_, B_, kt) do { _Pragma("unroll") for (int i = 0; i < 4; ++i) { \
;     A_[i] = *(const u32x4*)((const char*)Ap + (aoff + (unsigned)(32 * i * lda + (kt) * 64) * 2u)); B_[i] = *(const u32x4*)((const char*)Wt + (woff + (unsigned)(32 * i * K + (kt) * 64) * 2u)); } } while (0)
; #define BSTORE(A_, B_, buf) do { _Pragma("unroll") for (int i = 0; i < 4; ++i) { \
;     *(u32x4*)&As[(buf) * GBUF + (srow + 32 * i) * LDT + sc8] = A_[i]; \
;     *(u32x4*)&Bs[(buf) * GBUF + (srow + 32 * i) * LDT + sc8] = B_[i]; } } while (0)
; template <int NK>
; DI void gemm_run(PF& pf, const u16* __restrict__ Ap, int lda, const u16* __restrict__ Wt, f32x16 (&acc)[2][2], char* smem) {
;     ...
;   __builtin_amdgcn_s_setprio(0);
;   __syncthreads();
;   BSTORE(pf.a0, pf.b0, 0);
;   BLOAD(pf.a0, pf.b0, 2);
;   __syncthreads();
; #pragma unroll
;   for (int kt = 0; kt < nk; kt += 2) {
;     BCOMP(0);
;     BSTORE(pf.a1, pf.b1, 1);
;     if (kt + 3 < nk) BLOAD(pf.a1, pf.b1, kt + 3);
;     __syncthreads();
;     BCOMP(1);
;     if (kt + 2 < nk) { BSTORE(pf.a0, pf.b0, 0); if (kt + 4 < nk) BLOAD(pf.a0, pf.b0, kt + 4); }
;     __syncthreads();
;   }
	ds_read_b128 v[224:227], v126 offset:49152
	ds_read_b128 v[240:243], v128 offset:49152
	ds_read_b128 v[244:247], v128 offset:50176
	ds_read_b128 v[248:251], v128 offset:51200
	ds_read_b128 v[156:159], v128 offset:52224
	ds_read_b128 v[228:231], v126 offset:50176
	s_waitcnt lgkmcnt(4)
	v_mfma_f32_16x16x32_bf16 v[2:5], v[224:227], v[240:243], v[2:5]
	ds_read_b128 v[232:235], v126 offset:51200
	s_waitcnt lgkmcnt(4)
	v_mfma_f32_16x16x32_bf16 v[6:9], v[224:227], v[244:247], v[6:9]
	ds_read_b128 v[236:239], v126 offset:52224
	s_waitcnt lgkmcnt(4)
	v_mfma_f32_16x16x32_bf16 v[10:13], v[224:227], v[248:251], v[10:13]
	s_add_u32 m0, s46, 0x6000
	s_add_u32 s48, s48, 0x100000
	s_addc_u32 s49, s49, 0
	global_load_lds_dwordx4 v138, s[48:49]
	global_load_lds_dwordx4 v139, s[48:49] offset:1024
	s_add_u32 m0, s47, 0x6000
	s_add_u32 s50, s50, s13
	s_addc_u32 s51, s51, 0
	global_load_lds_dwordx4 v140, s[50:51]
	global_load_lds_dwordx4 v141, s[50:51] offset:1024
	global_load_lds_dwordx4 v142, s[50:51] offset:2048
	global_load_lds_dwordx4 v143, s[50:51] offset:3072
	s_waitcnt lgkmcnt(3)
	v_mfma_f32_16x16x32_bf16 v[14:17], v[224:227], v[156:159], v[14:17]
	s_waitcnt lgkmcnt(2)
	v_mfma_f32_16x16x32_bf16 v[18:21], v[228:231], v[240:243], v[18:21]
	ds_read_b128 v[160:163], v128 offset:57344
	v_mfma_f32_16x16x32_bf16 v[22:25], v[228:231], v[244:247], v[22:25]
	ds_read_b128 v[164:167], v128 offset:58368
	v_mfma_f32_16x16x32_bf16 v[26:29], v[228:231], v[248:251], v[26:29]
	ds_read_b128 v[168:171], v128 offset:59392
	v_mfma_f32_16x16x32_bf16 v[30:33], v[228:231], v[156:159], v[30:33]
	ds_read_b128 v[122:125], v128 offset:60416
	s_waitcnt lgkmcnt(5)
	v_mfma_f32_16x16x32_bf16 v[34:37], v[232:235], v[240:243], v[34:37]
	v_mfma_f32_16x16x32_bf16 v[38:41], v[232:235], v[244:247], v[38:41]
	v_mfma_f32_16x16x32_bf16 v[42:45], v[232:235], v[248:251], v[42:45]
	v_mfma_f32_16x16x32_bf16 v[46:49], v[232:235], v[156:159], v[46:49]
	s_waitcnt lgkmcnt(4)
	v_mfma_f32_16x16x32_bf16 v[50:53], v[236:239], v[240:243], v[50:53]
	v_mfma_f32_16x16x32_bf16 v[54:57], v[236:239], v[244:247], v[54:57]
	v_mfma_f32_16x16x32_bf16 v[58:61], v[236:239], v[248:251], v[58:61]
	v_mfma_f32_16x16x32_bf16 v[62:65], v[236:239], v[156:159], v[62:65]
	s_waitcnt lgkmcnt(3)
	v_mfma_f32_16x16x32_bf16 v[74:77], v[224:227], v[160:163], v[74:77]
	s_waitcnt lgkmcnt(2)
	v_mfma_f32_16x16x32_bf16 v[78:81], v[224:227], v[164:167], v[78:81]
	s_waitcnt lgkmcnt(1)
	v_mfma_f32_16x16x32_bf16 v[82:85], v[224:227], v[168:171], v[82:85]
	s_waitcnt lgkmcnt(0)
	v_mfma_f32_16x16x32_bf16 v[86:89], v[224:227], v[122:125], v[86:89]
	v_mfma_f32_16x16x32_bf16 v[90:93], v[228:231], v[160:163], v[90:93]
	v_mfma_f32_16x16x32_bf16 v[94:97], v[228:231], v[164:167], v[94:97]
	v_mfma_f32_16x16x32_bf16 v[98:101], v[228:231], v[168:171], v[98:101]
	v_mfma_f32_16x16x32_bf16 v[102:105], v[228:231], v[122:125], v[102:105]
	v_mfma_f32_16x16x32_bf16 v[106:109], v[232:235], v[160:163], v[106:109]
	v_mfma_f32_16x16x32_bf16 v[110:113], v[232:235], v[164:167], v[110:113]
	v_mfma_f32_16x16x32_bf16 v[114:117], v[232:235], v[168:171], v[114:117]
	v_mfma_f32_16x16x32_bf16 v[118:121], v[232:235], v[122:125], v[118:121]
	v_mfma_f32_16x16x32_bf16 v[208:211], v[236:239], v[160:163], v[208:211]
	v_mfma_f32_16x16x32_bf16 v[212:215], v[236:239], v[164:167], v[212:215]
	v_mfma_f32_16x16x32_bf16 v[216:219], v[236:239], v[168:171], v[216:219]
	v_mfma_f32_16x16x32_bf16 v[220:223], v[236:239], v[122:125], v[220:223]
	s_sub_u32 s12, s12, 1
	s_cmp_lg_u32 s12, 0
	s_cbranch_scc1 .Linp_kloop
	s_waitcnt vmcnt(6)
	s_barrier
; #define BLOAD(A_, B_, kt) do { _Pragma("unroll") for (int i = 0; i < 4; ++i) { \
;     A_[i] = *(const u32x4*)((const char*)Ap + (aoff + (unsigned)(32 * i * lda + (kt) * 64) * 2u)); B_[i] = *(const u32x4*)((const char*)Wt + (woff + (unsigned)(32 * i * K + (kt) * 64) * 2u)); } } while (0)
; #define BLOAD(A_, B_, kt) do { _Pragma("unroll") for (int i = 0; i < 4; ++i) { \
;     A_[i] = *(const u32x4*)((const char*)Ap + (aoff + (unsigned)(32 * i * lda + (kt) * 64) * 2u)); B_[i] = *(const u32x4*)((const char*)Wt + (woff + (unsigned)(32 * i * K + (kt) * 64) * 2u)); } } while (0)
; #define BSTORE(A_, B_, buf) do { _Pragma("unroll") for (int i = 0; i < 4; ++i) { \
;     *(u32x4*)&As[(buf) * GBUF + (srow + 32 * i) * LDT + sc8] = A_[i]; \
;     *(u32x4*)&Bs[(buf) * GBUF + (srow + 32 * i) * LDT + sc8] = B_[i]; } } while (0)
; template <int NK>
; DI void gemm_run(PF& pf, const u16* __restrict__ Ap, int lda, const u16* __restrict__ Wt, f32x16 (&acc)[2][2], char* smem) {
;     ...
;   __builtin_amdgcn_s_setprio(0);
;   __syncthreads();
;   BSTORE(pf.a0, pf.b0, 0);
;   BLOAD(pf.a0, pf.b0, 2);
;   __syncthreads();
; #pragma unroll
;   for (int kt = 0; kt < nk; kt += 2) {
;     BCOMP(0);
;     BSTORE(pf.a1, pf.b1, 1);
;     if (kt + 3 < nk) BLOAD(pf.a1, pf.b1, kt + 3);
;     __syncthreads();
;     BCOMP(1);
;     if (kt + 2 < nk) { BSTORE(pf.a0, pf.b0, 0); if (kt + 4 < nk) BLOAD(pf.a0, pf.b0, kt + 4); }
;     __syncthreads();
;   }
	ds_read_b128 v[224:227], v126 offset:0
	ds_read_b128 v[240:243], v128 offset:0
	ds_read_b128 v[244:247], v128 offset:1024
	ds_read_b128 v[248:251], v128 offset:2048
	ds_read_b128 v[156:159], v128 offset:3072
	ds_read_b128 v[228:231], v126 offset:1024
	s_waitcnt lgkmcnt(4)
	v_mfma_f32_16x16x32_bf16 v[2:5], v[224:227], v[240:243], v[2:5]
	ds_read_b128 v[232:235], v126 offset:2048
	s_waitcnt lgkmcnt(4)
	v_mfma_f32_16x16x32_bf16 v[6:9], v[224:227], v[244:247], v[6:9]
	ds_read_b128 v[236:239], v126 offset:3072
	s_waitcnt lgkmcnt(4)
	v_mfma_f32_16x16x32_bf16 v[10:13], v[224:227], v[248:251], v[10:13]
	s_waitcnt lgkmcnt(3)
	v_mfma_f32_16x16x32_bf16 v[14:17], v[224:227], v[156:159], v[14:17]
	s_waitcnt lgkmcnt(2)
	v_mfma_f32_16x16x32_bf16 v[18:21], v[228:231], v[240:243], v[18:21]
	ds_read_b128 v[160:163], v128 offset:8192
	v_mfma_f32_16x16x32_bf16 v[22:25], v[228:231], v[244:247], v[22:25]
	ds_read_b128 v[164:167], v128 offset:9216
	v_mfma_f32_16x16x32_bf16 v[26:29], v[228:231], v[248:251], v[26:29]
	ds_read_b128 v[168:171], v128 offset:10240
	v_mfma_f32_16x16x32_bf16 v[30:33], v[228:231], v[156:159], v[30:33]
	ds_read_b128 v[122:125], v128 offset:11264
	s_waitcnt lgkmcnt(5)
	v_mfma_f32_16x16x32_bf16 v[34:37], v[232:235], v[240:243], v[34:37]
	v_mfma_f32_16x16x32_bf16 v[38:41], v[232:235], v[244:247], v[38:41]
	v_mfma_f32_16x16x32_bf16 v[42:45], v[232:235], v[248:251], v[42:45]
	v_mfma_f32_16x16x32_bf16 v[46:49], v[232:235], v[156:159], v[46:49]
	s_waitcnt lgkmcnt(4)
	v_mfma_f32_16x16x32_bf16 v[50:53], v[236:239], v[240:243], v[50:53]
	v_mfma_f32_16x16x32_bf16 v[54:57], v[236:239], v[244:247], v[54:57]
	v_mfma_f32_16x16x32_bf16 v[58:61], v[236:239], v[248:251], v[58:61]
	v_mfma_f32_16x16x32_bf16 v[62:65], v[236:239], v[156:159], v[62:65]
	s_waitcnt lgkmcnt(3)
	v_mfma_f32_16x16x32_bf16 v[74:77], v[224:227], v[160:163], v[74:77]
	s_waitcnt lgkmcnt(2)
	v_mfma_f32_16x16x32_bf16 v[78:81], v[224:227], v[164:167], v[78:81]
	s_waitcnt lgkmcnt(1)
	v_mfma_f32_16x16x32_bf16 v[82:85], v[224:227], v[168:171], v[82:85]
	s_waitcnt lgkmcnt(0)
	v_mfma_f32_16x16x32_bf16 v[86:89], v[224:227], v[122:125], v[86:89]
	v_mfma_f32_16x16x32_bf16 v[90:93], v[228:231], v[160:163], v[90:93]
	v_mfma_f32_16x16x32_bf16 v[94:97], v[228:231], v[164:167], v[94:97]
	v_mfma_f32_16x16x32_bf16 v[98:101], v[228:231], v[168:171], v[98:101]
	v_mfma_f32_16x16x32_bf16 v[102:105], v[228:231], v[122:125], v[102:105]
	v_mfma_f32_16x16x32_bf16 v[106:109], v[232:235], v[160:163], v[106:109]
	v_mfma_f32_16x16x32_bf16 v[110:113], v[232:235], v[164:167], v[110:113]
	v_mfma_f32_16x16x32_bf16 v[114:117], v[232:235], v[168:171], v[114:117]
	v_mfma_f32_16x16x32_bf16 v[118:121], v[232:235], v[122:125], v[118:121]
	v_mfma_f32_16x16x32_bf16 v[208:211], v[236:239], v[160:163], v[208:211]
	v_mfma_f32_16x16x32_bf16 v[212:215], v[236:239], v[164:167], v[212:215]
	v_mfma_f32_16x16x32_bf16 v[216:219], v[236:239], v[168:171], v[216:219]
	v_mfma_f32_16x16x32_bf16 v[220:223], v[236:239], v[122:125], v[220:223]
	s_waitcnt vmcnt(0)
	s_barrier
	ds_read_b128 v[224:227], v126 offset:24576
	ds_read_b128 v[240:243], v128 offset:24576
	ds_read_b128 v[244:247], v128 offset:25600
	ds_read_b128 v[248:251], v128 offset:26624
	ds_read_b128 v[156:159], v128 offset:27648
	ds_read_b128 v[228:231], v126 offset:25600
	s_waitcnt lgkmcnt(4)
	v_mfma_f32_16x16x32_bf16 v[2:5], v[224:227], v[240:243], v[2:5]
	ds_read_b128 v[232:235], v126 offset:26624
	s_waitcnt lgkmcnt(4)
	v_mfma_f32_16x16x32_bf16 v[6:9], v[224:227], v[244:247], v[6:9]
	ds_read_b128 v[236:239], v126 offset:27648
	s_waitcnt lgkmcnt(4)
	v_mfma_f32_16x16x32_bf16 v[10:13], v[224:227], v[248:251], v[10:13]
	s_waitcnt lgkmcnt(3)
	v_mfma_f32_16x16x32_bf16 v[14:17], v[224:227], v[156:159], v[14:17]
	s_waitcnt lgkmcnt(2)
	v_mfma_f32_16x16x32_bf16 v[18:21], v[228:231], v[240:243], v[18:21]
	ds_read_b128 v[160:163], v128 offset:32768
	v_mfma_f32_16x16x32_bf16 v[22:25], v[228:231], v[244:247], v[22:25]
	ds_read_b128 v[164:167], v128 offset:33792
	v_mfma_f32_16x16x32_bf16 v[26:29], v[228:231], v[248:251], v[26:29]
	ds_read_b128 v[168:171], v128 offset:34816
	v_mfma_f32_16x16x32_bf16 v[30:33], v[228:231], v[156:159], v[30:33]
	ds_read_b128 v[122:125], v128 offset:35840
	s_waitcnt lgkmcnt(5)
	v_mfma_f32_16x16x32_bf16 v[34:37], v[232:235], v[240:243], v[34:37]
	v_mfma_f32_16x16x32_bf16 v[38:41], v[232:235], v[244:247], v[38:41]
	v_mfma_f32_16x16x32_bf16 v[42:45], v[232:235], v[248:251], v[42:45]
	v_mfma_f32_16x16x32_bf16 v[46:49], v[232:235], v[156:159], v[46:49]
	s_waitcnt lgkmcnt(4)
	v_mfma_f32_16x16x32_bf16 v[50:53], v[236:239], v[240:243], v[50:53]
	v_mfma_f32_16x16x32_bf16 v[54:57], v[236:239], v[244:247], v[54:57]
	v_mfma_f32_16x16x32_bf16 v[58:61], v[236:239], v[248:251], v[58:61]
	v_mfma_f32_16x16x32_bf16 v[62:65], v[236:239], v[156:159], v[62:65]
	s_waitcnt lgkmcnt(3)
	v_mfma_f32_16x16x32_bf16 v[74:77], v[224:227], v[160:163], v[74:77]
	s_waitcnt lgkmcnt(2)
	v_mfma_f32_16x16x32_bf16 v[78:81], v[224:227], v[164:167], v[78:81]
	s_waitcnt lgkmcnt(1)
	v_mfma_f32_16x16x32_bf16 v[82:85], v[224:227], v[168:171], v[82:85]
	s_waitcnt lgkmcnt(0)
	v_mfma_f32_16x16x32_bf16 v[86:89], v[224:227], v[122:125], v[86:89]
	v_mfma_f32_16x16x32_bf16 v[90:93], v[228:231], v[160:163], v[90:93]
	v_mfma_f32_16x16x32_bf16 v[94:97], v[228:231], v[164:167], v[94:97]
	v_mfma_f32_16x16x32_bf16 v[98:101], v[228:231], v[168:171], v[98:101]
	v_mfma_f32_16x16x32_bf16 v[102:105], v[228:231], v[122:125], v[102:105]
	v_mfma_f32_16x16x32_bf16 v[106:109], v[232:235], v[160:163], v[106:109]
	v_mfma_f32_16x16x32_bf16 v[110:113], v[232:235], v[164:167], v[110:113]
	v_mfma_f32_16x16x32_bf16 v[114:117], v[232:235], v[168:171], v[114:117]
	v_mfma_f32_16x16x32_bf16 v[118:121], v[232:235], v[122:125], v[118:121]
	v_mfma_f32_16x16x32_bf16 v[208:211], v[236:239], v[160:163], v[208:211]
	v_mfma_f32_16x16x32_bf16 v[212:215], v[236:239], v[164:167], v[212:215]
	v_mfma_f32_16x16x32_bf16 v[216:219], v[236:239], v[168:171], v[216:219]
	v_mfma_f32_16x16x32_bf16 v[220:223], v[236:239], v[122:125], v[220:223]
	s_barrier
	s_branch .Linp_post

; #define BLOAD(A_, B_, kt) do { _Pragma("unroll") for (int i = 0; i < 4; ++i) { \
;     A_[i] = *(const u32x4*)((const char*)Ap + (aoff + (unsigned)(32 * i * lda + (kt) * 64) * 2u)); B_[i] = *(const u32x4*)((const char*)Wt + (woff + (unsigned)(32 * i * K + (kt) * 64) * 2u)); } } while (0)
; #define BLOAD(A_, B_, kt) do { _Pragma("unroll") for (int i = 0; i < 4; ++i) { \
;     A_[i] = *(const u32x4*)((const char*)Ap + (aoff + (unsigned)(32 * i * lda + (kt) * 64) * 2u)); B_[i] = *(const u32x4*)((const char*)Wt + (woff + (unsigned)(32 * i * K + (kt) * 64) * 2u)); } } while (0)
; #define BSTORE(A_, B_, buf) do { _Pragma("unroll") for (int i = 0; i < 4; ++i) { \
;     *(u32x4*)&As[(buf) * GBUF + (srow + 32 * i) * LDT + sc8] = A_[i]; \
;     *(u32x4*)&Bs[(buf) * GBUF + (srow + 32 * i) * LDT + sc8] = B_[i]; } } while (0)
; template <int NK>
; DI void gemm_run(PF& pf, const u16* __restrict__ Ap, int lda, const u16* __restrict__ Wt, f32x16 (&acc)[2][2], char* smem) {
;     ...
;   __builtin_amdgcn_s_setprio(0);
;   __syncthreads();
;   BSTORE(pf.a0, pf.b0, 0);
;   BLOAD(pf.a0, pf.b0, 2);
;   __syncthreads();
; #pragma unroll
;   for (int kt = 0; kt < nk; kt += 2) {
;     BCOMP(0);
;     BSTORE(pf.a1, pf.b1, 1);
;     if (kt + 3 < nk) BLOAD(pf.a1, pf.b1, kt + 3);
;     __syncthreads();
;     BCOMP(1);
;     if (kt + 2 < nk) { BSTORE(pf.a0, pf.b0, 0); if (kt + 4 < nk) BLOAD(pf.a0, pf.b0, kt + 4); }
;     __syncthreads();
;   }
.Linpd_kloop:
	s_waitcnt vmcnt(6)
	s_barrier
	ds_read_b128 v[224:227], v126 offset:0
	ds_read_b128 v[240:243], v128 offset:0
	ds_read_b128 v[244:247], v128 offset:1024
	ds_read_b128 v[248:251], v128 offset:2048
	ds_read_b128 v[156:159], v128 offset:3072
	ds_read_b128 v[228:231], v126 offset:1024
	s_waitcnt lgkmcnt(4)
	v_mfma_f32_16x16x32_bf16 v[2:5], v[240:243], v[224:227], v[2:5]
	ds_read_b128 v[232:235], v126 offset:2048
	s_waitcnt lgkmcnt(4)
	v_mfma_f32_16x16x32_bf16 v[6:9], v[244:247], v[224:227], v[6:9]
	ds_read_b128 v[236:239], v126 offset:3072
	s_waitcnt lgkmcnt(4)
	v_mfma_f32_16x16x32_bf16 v[10:13], v[248:251], v[224:227], v[10:13]
	s_add_u32 m0, s46, 0xc000
	s_add_u32 s48, s48, 0x100000
	s_addc_u32 s49, s49, 0
	global_load_lds_dwordx4 v138, s[48:49]
	global_load_lds_dwordx4 v139, s[48:49] offset:1024
	s_add_u32 m0, s47, 0xc000
	s_add_u32 s50, s50, s13
	s_addc_u32 s51, s51, 0
	global_load_lds_dwordx4 v140, s[50:51]
	global_load_lds_dwordx4 v141, s[50:51] offset:1024
	global_load_lds_dwordx4 v142, s[50:51] offset:2048
	global_load_lds_dwordx4 v143, s[50:51] offset:3072
	s_waitcnt lgkmcnt(3)
	v_mfma_f32_16x16x32_bf16 v[14:17], v[156:159], v[224:227], v[14:17]
	s_waitcnt lgkmcnt(2)
	v_mfma_f32_16x16x32_bf16 v[18:21], v[240:243], v[228:231], v[18:21]
	ds_read_b128 v[160:163], v128 offset:8192
	v_mfma_f32_16x16x32_bf16 v[22:25], v[244:247], v[228:231], v[22:25]
	ds_read_b128 v[164:167], v128 offset:9216
	v_mfma_f32_16x16x32_bf16 v[26:29], v[248:251], v[228:231], v[26:29]
	ds_read_b128 v[168:171], v128 offset:10240
	v_mfma_f32_16x16x32_bf16 v[30:33], v[156:159], v[228:231], v[30:33]
	ds_read_b128 v[122:125], v128 offset:11264
	s_waitcnt lgkmcnt(5)
	v_mfma_f32_16x16x32_bf16 v[34:37], v[240:243], v[232:235], v[34:37]
	v_mfma_f32_16x16x32_bf16 v[38:41], v[244:247], v[232:235], v[38:41]
	v_mfma_f32_16x16x32_bf16 v[42:45], v[248:251], v[232:235], v[42:45]
	v_mfma_f32_16x16x32_bf16 v[46:49], v[156:159], v[232:235], v[46:49]
	s_waitcnt lgkmcnt(4)
	v_mfma_f32_16x16x32_bf16 v[50:53], v[240:243], v[236:239], v[50:53]
	v_mfma_f32_16x16x32_bf16 v[54:57], v[244:247], v[236:239], v[54:57]
	v_mfma_f32_16x16x32_bf16 v[58:61], v[248:251], v[236:239], v[58:61]
	v_mfma_f32_16x16x32_bf16 v[62:65], v[156:159], v[236:239], v[62:65]
	s_waitcnt lgkmcnt(3)
	v_mfma_f32_16x16x32_bf16 v[74:77], v[160:163], v[224:227], v[74:77]
	s_waitcnt lgkmcnt(2)
	v_mfma_f32_16x16x32_bf16 v[78:81], v[164:167], v[224:227], v[78:81]
	s_waitcnt lgkmcnt(1)
	v_mfma_f32_16x16x32_bf16 v[82:85], v[168:171], v[224:227], v[82:85]
	s_waitcnt lgkmcnt(0)
	v_mfma_f32_16x16x32_bf16 v[86:89], v[122:125], v[224:227], v[86:89]
	v_mfma_f32_16x16x32_bf16 v[90:93], v[160:163], v[228:231], v[90:93]
	v_mfma_f32_16x16x32_bf16 v[94:97], v[164:167], v[228:231], v[94:97]
	v_mfma_f32_16x16x32_bf16 v[98:101], v[168:171], v[228:231], v[98:101]
	v_mfma_f32_16x16x32_bf16 v[102:105], v[122:125], v[228:231], v[102:105]
	v_mfma_f32_16x16x32_bf16 v[106:109], v[160:163], v[232:235], v[106:109]
	v_mfma_f32_16x16x32_bf16 v[110:113], v[164:167], v[232:235], v[110:113]
	v_mfma_f32_16x16x32_bf16 v[114:117], v[168:171], v[232:235], v[114:117]
	v_mfma_f32_16x16x32_bf16 v[118:121], v[122:125], v[232:235], v[118:121]
	v_mfma_f32_16x16x32_bf16 v[208:211], v[160:163], v[236:239], v[208:211]
	v_mfma_f32_16x16x32_bf16 v[212:215], v[164:167], v[236:239], v[212:215]
	v_mfma_f32_16x16x32_bf16 v[216:219], v[168:171], v[236:239], v[216:219]
	v_mfma_f32_16x16x32_bf16 v[220:223], v[122:125], v[236:239], v[220:223]
	s_waitcnt vmcnt(6)
	s_barrier
	ds_read_b128 v[224:227], v126 offset:24576
	ds_read_b128 v[240:243], v128 offset:24576
	ds_read_b128 v[244:247], v128 offset:25600
	ds_read_b128 v[248:251], v128 offset:26624
	ds_read_b128 v[156:159], v128 offset:27648
	ds_read_b128 v[228:231], v126 offset:25600
	s_waitcnt lgkmcnt(4)
	v_mfma_f32_16x16x32_bf16 v[2:5], v[240:243], v[224:227], v[2:5]
	ds_read_b128 v[232:235], v126 offset:26624
	s_waitcnt lgkmcnt(4)
	v_mfma_f32_16x16x32_bf16 v[6:9], v[244:247], v[224:227], v[6:9]
	ds_read_b128 v[236:239], v126 offset:27648
	s_waitcnt lgkmcnt(4)
	v_mfma_f32_16x16x32_bf16 v[10:13], v[248:251], v[224:227], v[10:13]
	s_add_u32 m0, s46, 0x0
	s_add_u32 s48, s48, 0x100000
	s_addc_u32 s49, s49, 0
	global_load_lds_dwordx4 v138, s[48:49]
	global_load_lds_dwordx4 v139, s[48:49] offset:1024
	s_add_u32 m0, s47, 0x0
	s_add_u32 s50, s50, s13
	s_addc_u32 s51, s51, 0
	global_load_lds_dwordx4 v140, s[50:51]
	global_load_lds_dwordx4 v141, s[50:51] offset:1024
	global_load_lds_dwordx4 v142, s[50:51] offset:2048
	global_load_lds_dwordx4 v143, s[50:51] offset:3072
	s_waitcnt lgkmcnt(3)
	v_mfma_f32_16x16x32_bf16 v[14:17], v[156:159], v[224:227], v[14:17]
	s_waitcnt lgkmcnt(2)
	v_mfma_f32_16x16x32_bf16 v[18:21], v[240:243], v[228:231], v[18:21]
	ds_read_b128 v[160:163], v128 offset:32768
	v_mfma_f32_16x16x32_bf16 v[22:25], v[244:247], v[228:231], v[22:25]
	ds_read_b128 v[164:167], v128 offset:33792
	v_mfma_f32_16x16x32_bf16 v[26:29], v[248:251], v[228:231], v[26:29]
	ds_read_b128 v[168:171], v128 offset:34816
	v_mfma_f32_16x16x32_bf16 v[30:33], v[156:159], v[228:231], v[30:33]
	ds_read_b128 v[122:125], v128 offset:35840
	s_waitcnt lgkmcnt(5)
	v_mfma_f32_16x16x32_bf16 v[34:37], v[240:243], v[232:235], v[34:37]
	v_mfma_f32_16x16x32_bf16 v[38:41], v[244:247], v[232:235], v[38:41]
	v_mfma_f32_16x16x32_bf16 v[42:45], v[248:251], v[232:235], v[42:45]
	v_mfma_f32_16x16x32_bf16 v[46:49], v[156:159], v[232:235], v[46:49]
	s_waitcnt lgkmcnt(4)
	v_mfma_f32_16x16x32_bf16 v[50:53], v[240:243], v[236:239], v[50:53]
	v_mfma_f32_16x16x32_bf16 v[54:57], v[244:247], v[236:239], v[54:57]
	v_mfma_f32_16x16x32_bf16 v[58:61], v[248:251], v[236:239], v[58:61]
	v_mfma_f32_16x16x32_bf16 v[62:65], v[156:159], v[236:239], v[62:65]
	s_waitcnt lgkmcnt(3)
	v_mfma_f32_16x16x32_bf16 v[74:77], v[160:163], v[224:227], v[74:77]
	s_waitcnt lgkmcnt(2)
	v_mfma_f32_16x16x32_bf16 v[78:81], v[164:167], v[224:227], v[78:81]
	s_waitcnt lgkmcnt(1)
	v_mfma_f32_16x16x32_bf16 v[82:85], v[168:171], v[224:227], v[82:85]
	s_waitcnt lgkmcnt(0)
	v_mfma_f32_16x16x32_bf16 v[86:89], v[122:125], v[224:227], v[86:89]
	v_mfma_f32_16x16x32_bf16 v[90:93], v[160:163], v[228:231], v[90:93]
	v_mfma_f32_16x16x32_bf16 v[94:97], v[164:167], v[228:231], v[94:97]
	v_mfma_f32_16x16x32_bf16 v[98:101], v[168:171], v[228:231], v[98:101]
	v_mfma_f32_16x16x32_bf16 v[102:105], v[122:125], v[228:231], v[102:105]
	v_mfma_f32_16x16x32_bf16 v[106:109], v[160:163], v[232:235], v[106:109]
	v_mfma_f32_16x16x32_bf16 v[110:113], v[164:167], v[232:235], v[110:113]
	v_mfma_f32_16x16x32_bf16 v[114:117], v[168:171], v[232:235], v[114:117]
	v_mfma_f32_16x16x32_bf16 v[118:121], v[122:125], v[232:235], v[118:121]
	v_mfma_f32_16x16x32_bf16 v[208:211], v[160:163], v[236:239], v[208:211]
	v_mfma_f32_16x16x32_bf16 v[212:215], v[164:167], v[236:239], v[212:215]
	v_mfma_f32_16x16x32_bf16 v[216:219], v[168:171], v[236:239], v[216:219]
	v_mfma_f32_16x16x32_bf16 v[220:223], v[122:125], v[236:239], v[220:223]
	s_waitcnt vmcnt(6)
	s_barrier
; #define BLOAD(A_, B_, kt) do { _Pragma("unroll") for (int i = 0; i < 4; ++i) { \
;     A_[i] = *(const u32x4*)((const char*)Ap + (aoff + (unsigned)(32 * i * lda + (kt) * 64) * 2u)); B_[i] = *(const u32x4*)((const char*)Wt + (woff + (unsigned)(32 * i * K + (kt) * 64) * 2u)); } } while (0)
; #define BLOAD(A_, B_, kt) do { _Pragma("unroll") for (int i = 0; i < 4; ++i) { \
;     A_[i] = *(const u32x4*)((const char*)Ap + (aoff + (unsigned)(32 * i * lda + (kt) * 64) * 2u)); B_[i] = *(const u32x4*)((const char*)Wt + (woff + (unsigned)(32 * i * K + (kt) * 64) * 2u)); } } while (0)
; #define BSTORE(A_, B_, buf) do { _Pragma("unroll") for (int i = 0; i < 4; ++i) { \
;     *(u32x4*)&As[(buf) * GBUF + (srow + 32 * i) * LDT + sc8] = A_[i]; \
;     *(u32x4*)&Bs[(buf) * GBUF + (srow + 32 * i) * LDT + sc8] = B_[i]; } } while (0)
; template <int NK>
; DI void gemm_run(PF& pf, const u16* __restrict__ Ap, int lda, const u16* __restrict__ Wt, f32x16 (&acc)[2][2], char* smem) {
;     ...
;   __builtin_amdgcn_s_setprio(0);
;   __syncthreads();
;   BSTORE(pf.a0, pf.b0, 0);
;   BLOAD(pf.a0, pf.b0, 2);
;   __syncthreads();
; #pragma unroll
;   for (int kt = 0; kt < nk; kt += 2) {
;     BCOMP(0);
;     BSTORE(pf.a1, pf.b1, 1);
;     if (kt + 3 < nk) BLOAD(pf.a1, pf.b1, kt + 3);
;     __syncthreads();
;     BCOMP(1);
;     if (kt + 2 < nk) { BSTORE(pf.a0, pf.b0, 0); if (kt + 4 < nk) BLOAD(pf.a0, pf.b0, kt + 4); }
;     __syncthreads();
;   }
	ds_read_b128 v[224:227], v126 offset:49152
	ds_read_b128 v[240:243], v128 offset:49152
	ds_read_b128 v[244:247], v128 offset:50176
	ds_read_b128 v[248:251], v128 offset:51200
	ds_read_b128 v[156:159], v128 offset:52224
	ds_read_b128 v[228:231], v126 offset:50176
	s_waitcnt lgkmcnt(4)
	v_mfma_f32_16x16x32_bf16 v[2:5], v[240:243], v[224:227], v[2:5]
	ds_read_b128 v[232:235], v126 offset:51200
	s_waitcnt lgkmcnt(4)
	v_mfma_f32_16x16x32_bf16 v[6:9], v[244:247], v[224:227], v[6:9]
	ds_read_b128 v[236:239], v126 offset:52224
	s_waitcnt lgkmcnt(4)
	v_mfma_f32_16x16x32_bf16 v[10:13], v[248:251], v[224:227], v[10:13]
	s_add_u32 m0, s46, 0x6000
	s_add_u32 s48, s48, 0x100000
	s_addc_u32 s49, s49, 0
	global_load_lds_dwordx4 v138, s[48:49]
	global_load_lds_dwordx4 v139, s[48:49] offset:1024
	s_add_u32 m0, s47, 0x6000
	s_add_u32 s50, s50, s13
	s_addc_u32 s51, s51, 0
	global_load_lds_dwordx4 v140, s[50:51]
	global_load_lds_dwordx4 v141, s[50:51] offset:1024
	global_load_lds_dwordx4 v142, s[50:51] offset:2048
	global_load_lds_dwordx4 v143, s[50:51] offset:3072
	s_waitcnt lgkmcnt(3)
	v_mfma_f32_16x16x32_bf16 v[14:17], v[156:159], v[224:227], v[14:17]
	s_waitcnt lgkmcnt(2)
	v_mfma_f32_16x16x32_bf16 v[18:21], v[240:243], v[228:231], v[18:21]
	ds_read_b128 v[160:163], v128 offset:57344
	v_mfma_f32_16x16x32_bf16 v[22:25], v[244:247], v[228:231], v[22:25]
	ds_read_b128 v[164:167], v128 offset:58368
	v_mfma_f32_16x16x32_bf16 v[26:29], v[248:251], v[228:231], v[26:29]
	ds_read_b128 v[168:171], v128 offset:59392
	v_mfma_f32_16x16x32_bf16 v[30:33], v[156:159], v[228:231], v[30:33]
	ds_read_b128 v[122:125], v128 offset:60416
	s_waitcnt lgkmcnt(5)
	v_mfma_f32_16x16x32_bf16 v[34:37], v[240:243], v[232:235], v[34:37]
	v_mfma_f32_16x16x32_bf16 v[38:41], v[244:247], v[232:235], v[38:41]
	v_mfma_f32_16x16x32_bf16 v[42:45], v[248:251], v[232:235], v[42:45]
	v_mfma_f32_16x16x32_bf16 v[46:49], v[156:159], v[232:235], v[46:49]
	s_waitcnt lgkmcnt(4)
	v_mfma_f32_16x16x32_bf16 v[50:53], v[240:243], v[236:239], v[50:53]
	v_mfma_f32_16x16x32_bf16 v[54:57], v[244:247], v[236:239], v[54:57]
	v_mfma_f32_16x16x32_bf16 v[58:61], v[248:251], v[236:239], v[58:61]
	v_mfma_f32_16x16x32_bf16 v[62:65], v[156:159], v[236:239], v[62:65]
	s_waitcnt lgkmcnt(3)
	v_mfma_f32_16x16x32_bf16 v[74:77], v[160:163], v[224:227], v[74:77]
	s_waitcnt lgkmcnt(2)
	v_mfma_f32_16x16x32_bf16 v[78:81], v[164:167], v[224:227], v[78:81]
	s_waitcnt lgkmcnt(1)
	v_mfma_f32_16x16x32_bf16 v[82:85], v[168:171], v[224:227], v[82:85]
	s_waitcnt lgkmcnt(0)
	v_mfma_f32_16x16x32_bf16 v[86:89], v[122:125], v[224:227], v[86:89]
	v_mfma_f32_16x16x32_bf16 v[90:93], v[160:163], v[228:231], v[90:93]
	v_mfma_f32_16x16x32_bf16 v[94:97], v[164:167], v[228:231], v[94:97]
	v_mfma_f32_16x16x32_bf16 v[98:101], v[168:171], v[228:231], v[98:101]
	v_mfma_f32_16x16x32_bf16 v[102:105], v[122:125], v[228:231], v[102:105]
	v_mfma_f32_16x16x32_bf16 v[106:109], v[160:163], v[232:235], v[106:109]
	v_mfma_f32_16x16x32_bf16 v[110:113], v[164:167], v[232:235], v[110:113]
	v_mfma_f32_16x16x32_bf16 v[114:117], v[168:171], v[232:235], v[114:117]
	v_mfma_f32_16x16x32_bf16 v[118:121], v[122:125], v[232:235], v[118:121]
	v_mfma_f32_16x16x32_bf16 v[208:211], v[160:163], v[236:239], v[208:211]
	v_mfma_f32_16x16x32_bf16 v[212:215], v[164:167], v[236:239], v[212:215]
	v_mfma_f32_16x16x32_bf16 v[216:219], v[168:171], v[236:239], v[216:219]
	v_mfma_f32_16x16x32_bf16 v[220:223], v[122:125], v[236:239], v[220:223]
	s_sub_u32 s12, s12, 1
	s_cmp_lg_u32 s12, 0
	s_cbranch_scc1 .Linpd_kloop
	s_waitcnt vmcnt(6)
	s_barrier
; #define BLOAD(A_, B_, kt) do { _Pragma("unroll") for (int i = 0; i < 4; ++i) { \
;     A_[i] = *(const u32x4*)((const char*)Ap + (aoff + (unsigned)(32 * i * lda + (kt) * 64) * 2u)); B_[i] = *(const u32x4*)((const char*)Wt + (woff + (unsigned)(32 * i * K + (kt) * 64) * 2u)); } } while (0)
; #define BLOAD(A_, B_, kt) do { _Pragma("unroll") for (int i = 0; i < 4; ++i) { \
;     A_[i] = *(const u32x4*)((const char*)Ap + (aoff + (unsigned)(32 * i * lda + (kt) * 64) * 2u)); B_[i] = *(const u32x4*)((const char*)Wt + (woff + (unsigned)(32 * i * K + (kt) * 64) * 2u)); } } while (0)
; #define BSTORE(A_, B_, buf) do { _Pragma("unroll") for (int i = 0; i < 4; ++i) { \
;     *(u32x4*)&As[(buf) * GBUF + (srow + 32 * i) * LDT + sc8] = A_[i]; \
;     *(u32x4*)&Bs[(buf) * GBUF + (srow + 32 * i) * LDT + sc8] = B_[i]; } } while (0)
; template <int NK>
; DI void gemm_run(PF& pf, const u16* __restrict__ Ap, int lda, const u16* __restrict__ Wt, f32x16 (&acc)[2][2], char* smem) {
;     ...
;   __builtin_amdgcn_s_setprio(0);
;   __syncthreads();
;   BSTORE(pf.a0, pf.b0, 0);
;   BLOAD(pf.a0, pf.b0, 2);
;   __syncthreads();
; #pragma unroll
;   for (int kt = 0; kt < nk; kt += 2) {
;     BCOMP(0);
;     BSTORE(pf.a1, pf.b1, 1);
;     if (kt + 3 < nk) BLOAD(pf.a1, pf.b1, kt + 3);
;     __syncthreads();
;     BCOMP(1);
;     if (kt + 2 < nk) { BSTORE(pf.a0, pf.b0, 0); if (kt + 4 < nk) BLOAD(pf.a0, pf.b0, kt + 4); }
;     __syncthreads();
;   }
	ds_read_b128 v[224:227], v126 offset:0
	ds_read_b128 v[240:243], v128 offset:0
	ds_read_b128 v[244:247], v128 offset:1024
	ds_read_b128 v[248:251], v128 offset:2048
	ds_read_b128 v[156:159], v128 offset:3072
	ds_read_b128 v[228:231], v126 offset:1024
	s_waitcnt lgkmcnt(4)
	v_mfma_f32_16x16x32_bf16 v[2:5], v[240:243], v[224:227], v[2:5]
	ds_read_b128 v[232:235], v126 offset:2048
	s_waitcnt lgkmcnt(4)
	v_mfma_f32_16x16x32_bf16 v[6:9], v[244:247], v[224:227], v[6:9]
	ds_read_b128 v[236:239], v126 offset:3072
	s_waitcnt lgkmcnt(4)
	v_mfma_f32_16x16x32_bf16 v[10:13], v[248:251], v[224:227], v[10:13]
	s_waitcnt lgkmcnt(3)
	v_mfma_f32_16x16x32_bf16 v[14:17], v[156:159], v[224:227], v[14:17]
	s_waitcnt lgkmcnt(2)
	v_mfma_f32_16x16x32_bf16 v[18:21], v[240:243], v[228:231], v[18:21]
	ds_read_b128 v[160:163], v128 offset:8192
	v_mfma_f32_16x16x32_bf16 v[22:25], v[244:247], v[228:231], v[22:25]
	ds_read_b128 v[164:167], v128 offset:9216
	v_mfma_f32_16x16x32_bf16 v[26:29], v[248:251], v[228:231], v[26:29]
	ds_read_b128 v[168:171], v128 offset:10240
	v_mfma_f32_16x16x32_bf16 v[30:33], v[156:159], v[228:231], v[30:33]
	ds_read_b128 v[122:125], v128 offset:11264
	s_waitcnt lgkmcnt(5)
	v_mfma_f32_16x16x32_bf16 v[34:37], v[240:243], v[232:235], v[34:37]
	v_mfma_f32_16x16x32_bf16 v[38:41], v[244:247], v[232:235], v[38:41]
	v_mfma_f32_16x16x32_bf16 v[42:45], v[248:251], v[232:235], v[42:45]
	v_mfma_f32_16x16x32_bf16 v[46:49], v[156:159], v[232:235], v[46:49]
	s_waitcnt lgkmcnt(4)
	v_mfma_f32_16x16x32_bf16 v[50:53], v[240:243], v[236:239], v[50:53]
	v_mfma_f32_16x16x32_bf16 v[54:57], v[244:247], v[236:239], v[54:57]
	v_mfma_f32_16x16x32_bf16 v[58:61], v[248:251], v[236:239], v[58:61]
	v_mfma_f32_16x16x32_bf16 v[62:65], v[156:159], v[236:239], v[62:65]
	s_waitcnt lgkmcnt(3)
	v_mfma_f32_16x16x32_bf16 v[74:77], v[160:163], v[224:227], v[74:77]
	s_waitcnt lgkmcnt(2)
	v_mfma_f32_16x16x32_bf16 v[78:81], v[164:167], v[224:227], v[78:81]
	s_waitcnt lgkmcnt(1)
	v_mfma_f32_16x16x32_bf16 v[82:85], v[168:171], v[224:227], v[82:85]
	s_waitcnt lgkmcnt(0)
	v_mfma_f32_16x16x32_bf16 v[86:89], v[122:125], v[224:227], v[86:89]
	v_mfma_f32_16x16x32_bf16 v[90:93], v[160:163], v[228:231], v[90:93]
	v_mfma_f32_16x16x32_bf16 v[94:97], v[164:167], v[228:231], v[94:97]
	v_mfma_f32_16x16x32_bf16 v[98:101], v[168:171], v[228:231], v[98:101]
	v_mfma_f32_16x16x32_bf16 v[102:105], v[122:125], v[228:231], v[102:105]
	v_mfma_f32_16x16x32_bf16 v[106:109], v[160:163], v[232:235], v[106:109]
	v_mfma_f32_16x16x32_bf16 v[110:113], v[164:167], v[232:235], v[110:113]
	v_mfma_f32_16x16x32_bf16 v[114:117], v[168:171], v[232:235], v[114:117]
	v_mfma_f32_16x16x32_bf16 v[118:121], v[122:125], v[232:235], v[118:121]
	v_mfma_f32_16x16x32_bf16 v[208:211], v[160:163], v[236:239], v[208:211]
	v_mfma_f32_16x16x32_bf16 v[212:215], v[164:167], v[236:239], v[212:215]
	v_mfma_f32_16x16x32_bf16 v[216:219], v[168:171], v[236:239], v[216:219]
	v_mfma_f32_16x16x32_bf16 v[220:223], v[122:125], v[236:239], v[220:223]
	s_waitcnt vmcnt(0)
	s_barrier
	ds_read_b128 v[224:227], v126 offset:24576
	ds_read_b128 v[240:243], v128 offset:24576
	ds_read_b128 v[244:247], v128 offset:25600
	ds_read_b128 v[248:251], v128 offset:26624
	ds_read_b128 v[156:159], v128 offset:27648
	ds_read_b128 v[228:231], v126 offset:25600
	s_waitcnt lgkmcnt(4)
	v_mfma_f32_16x16x32_bf16 v[2:5], v[240:243], v[224:227], v[2:5]
	ds_read_b128 v[232:235], v126 offset:26624
	s_waitcnt lgkmcnt(4)
	v_mfma_f32_16x16x32_bf16 v[6:9], v[244:247], v[224:227], v[6:9]
	ds_read_b128 v[236:239], v126 offset:27648
	s_waitcnt lgkmcnt(4)
	v_mfma_f32_16x16x32_bf16 v[10:13], v[248:251], v[224:227], v[10:13]
	s_waitcnt lgkmcnt(3)
	v_mfma_f32_16x16x32_bf16 v[14:17], v[156:159], v[224:227], v[14:17]
	s_waitcnt lgkmcnt(2)
	v_mfma_f32_16x16x32_bf16 v[18:21], v[240:243], v[228:231], v[18:21]
	ds_read_b128 v[160:163], v128 offset:32768
	v_mfma_f32_16x16x32_bf16 v[22:25], v[244:247], v[228:231], v[22:25]
	ds_read_b128 v[164:167], v128 offset:33792
	v_mfma_f32_16x16x32_bf16 v[26:29], v[248:251], v[228:231], v[26:29]
	ds_read_b128 v[168:171], v128 offset:34816
	v_mfma_f32_16x16x32_bf16 v[30:33], v[156:159], v[228:231], v[30:33]
	ds_read_b128 v[122:125], v128 offset:35840
	s_waitcnt lgkmcnt(5)
	v_mfma_f32_16x16x32_bf16 v[34:37], v[240:243], v[232:235], v[34:37]
	v_mfma_f32_16x16x32_bf16 v[38:41], v[244:247], v[232:235], v[38:41]
	v_mfma_f32_16x16x32_bf16 v[42:45], v[248:251], v[232:235], v[42:45]
	v_mfma_f32_16x16x32_bf16 v[46:49], v[156:159], v[232:235], v[46:49]
	s_waitcnt lgkmcnt(4)
	v_mfma_f32_16x16x32_bf16 v[50:53], v[240:243], v[236:239], v[50:53]
	v_mfma_f32_16x16x32_bf16 v[54:57], v[244:247], v[236:239], v[54:57]
	v_mfma_f32_16x16x32_bf16 v[58:61], v[248:251], v[236:239], v[58:61]
	v_mfma_f32_16x16x32_bf16 v[62:65], v[156:159], v[236:239], v[62:65]
	s_waitcnt lgkmcnt(3)
	v_mfma_f32_16x16x32_bf16 v[74:77], v[160:163], v[224:227], v[74:77]
	s_waitcnt lgkmcnt(2)
	v_mfma_f32_16x16x32_bf16 v[78:81], v[164:167], v[224:227], v[78:81]
	s_waitcnt lgkmcnt(1)
	v_mfma_f32_16x16x32_bf16 v[82:85], v[168:171], v[224:227], v[82:85]
	s_waitcnt lgkmcnt(0)
	v_mfma_f32_16x16x32_bf16 v[86:89], v[122:125], v[224:227], v[86:89]
	v_mfma_f32_16x16x32_bf16 v[90:93], v[160:163], v[228:231], v[90:93]
	v_mfma_f32_16x16x32_bf16 v[94:97], v[164:167], v[228:231], v[94:97]
	v_mfma_f32_16x16x32_bf16 v[98:101], v[168:171], v[228:231], v[98:101]
	v_mfma_f32_16x16x32_bf16 v[102:105], v[122:125], v[228:231], v[102:105]
	v_mfma_f32_16x16x32_bf16 v[106:109], v[160:163], v[232:235], v[106:109]
	v_mfma_f32_16x16x32_bf16 v[110:113], v[164:167], v[232:235], v[110:113]
	v_mfma_f32_16x16x32_bf16 v[114:117], v[168:171], v[232:235], v[114:117]
	v_mfma_f32_16x16x32_bf16 v[118:121], v[122:125], v[232:235], v[118:121]
	v_mfma_f32_16x16x32_bf16 v[208:211], v[160:163], v[236:239], v[208:211]
	v_mfma_f32_16x16x32_bf16 v[212:215], v[164:167], v[236:239], v[212:215]
	v_mfma_f32_16x16x32_bf16 v[216:219], v[168:171], v[236:239], v[216:219]
	v_mfma_f32_16x16x32_bf16 v[220:223], v[122:125], v[236:239], v[220:223]
	s_barrier
	s_branch .Linp_post
